# GEMM K-loops: the load segment's LDS-read wait moved from before the phase barrier to the first MFMA after it (waits to first consumer)
# speedup vs baseline: 1.0041x; 1.0002x over previous
; #define PG8_STAGE(bufoff, gbase, voff) do { _Pragma("unroll") for (int _i = 0; _i < 2; ++_i) \
;         __builtin_amdgcn_global_load_lds((const unsigned*)((const char*)(gbase) + (voff)[_i]), (PG8_LAS unsigned*)(lds + (bufoff) + ldsw + _i * 8192), 16, 0, 0); } while (0)
; #define PG8_LDA(dst, b, h) do { _Pragma("unroll") for (int m = 0; m < 4; ++m) _Pragma("unroll") for (int k = 0; k < 2; ++k) dst[m][k] = *(const PG8_LAS bf16x8*)(lds + PG8_SA(b, h) + aoff + m * 2048 + k * 1024); } while (0)
; #define PG8_LDB(dst, b, h) do { _Pragma("unroll") for (int n = 0; n < 2; ++n) _Pragma("unroll") for (int k = 0; k < 2; ++k) dst[n][k] = *(const PG8_LAS bf16x8*)(lds + PG8_SB(b, h) + boff + n * 2048 + k * 1024); } while (0)
; #define PG8_MMA(ai, bj, At, Bt) do { __builtin_amdgcn_s_setprio(1); _Pragma("unroll") for (int m = 0; m < 4; ++m) _Pragma("unroll") for (int n = 0; n < 2; ++n) _Pragma("unroll") for (int k = 0; k < 2; ++k) \
;         acc[ai][bj][m][n] = __builtin_amdgcn_mfma_f32_16x16x32_bf16(Bt[n][k], At[m][k], acc[ai][bj][m][n], 0, 0, 0); __builtin_amdgcn_s_setprio(0); } while (0)
; #define PG8_WAIT_V(n) asm volatile("s_waitcnt vmcnt(" #n ")" ::: "memory")
; #define PG8_WAIT_L(n) asm volatile("s_waitcnt lgkmcnt(" #n ")" ::: "memory")
; #define PG8_BAR __builtin_amdgcn_s_barrier()
; #define PG8_SCHED __builtin_amdgcn_sched_barrier(0)
; template <class Epi, class Sched, bool ALIGN_EPI = false, bool SP2 = false>
; __device__ __forceinline__ void gemm_phase(PG8_LAS unsigned char* lds, const Gemm g, const Sched& S, const Epi& E) {
;     ...
;             PG8_LDB(B0, 0, 0); PG8_LDB(B1, 0, 1); PG8_SCHED; PG8_LDA(At, 0, 0); PG8_STAGE(PG8_SA(1, 1), a1 + hstep, voffA);
;             PG8_WAIT_V(8); PG8_WAIT_L(0); PG8_BAR; PG8_MMA(0, 0, At, B0); PG8_MMA(0, 1, At, B1); PG8_BAR; PG8_SCHED;
;             PG8_LDA(At, 0, 1); PG8_STAGE(PG8_SB(0, 0), b2, voffB); PG8_STAGE(PG8_SB(0, 1), b2 + hstep, voffB); PG8_STAGE(PG8_SA(0, 0), a2, voffA);
;             PG8_WAIT_V(8); PG8_WAIT_L(0); PG8_BAR; PG8_MMA(1, 0, At, B0); PG8_MMA(1, 1, At, B1); PG8_BAR; PG8_SCHED;
.Lprio_done_86:
.LBB0_86:
	s_add_u32 s26, s38, 0xfff80080
	s_addc_u32 s27, s39, -1
	s_add_i32 s55, 0, 0x10000
	s_cmp_eq_u32 s54, 28
	s_cselect_b32 s27, s29, s27
	s_cselect_b32 s26, s50, s26
	v_add_u32_e32 v142, s55, v147
	s_cselect_b32 s41, s19, s53
	s_cselect_b32 s40, s51, s52
	s_add_i32 s58, 0, 0x14000
	ds_read_b128 v[148:151], v142
	ds_read_b128 v[156:159], v142 offset:1024
	ds_read_b128 v[160:163], v142 offset:2048
	ds_read_b128 v[164:167], v142 offset:3072
	v_add_u32_e32 v142, s58, v147
	ds_read_b128 v[168:171], v142
	ds_read_b128 v[184:187], v142 offset:1024
	ds_read_b128 v[188:191], v142 offset:2048
	ds_read_b128 v[192:195], v142 offset:3072
	v_lshl_add_u64 v[144:145], s[38:39], 0, v[140:141]
	s_add_i32 m0, s25, 0xc000
	ds_read_b128 v[196:199], v155
	ds_read_b128 v[200:203], v155 offset:1024
	ds_read_b128 v[204:207], v155 offset:2048
	ds_read_b128 v[208:211], v155 offset:3072
	ds_read_b128 v[212:215], v155 offset:4096
	ds_read_b128 v[216:219], v155 offset:5120
	ds_read_b128 v[220:223], v155 offset:6144
	ds_read_b128 v[224:227], v155 offset:7168
	global_load_lds_dwordx4 v[144:145], off
	v_lshl_add_u64 v[144:145], s[38:39], 0, v[138:139]
	s_add_i32 m0, s25, 0xe000
	s_nop 0
	global_load_lds_dwordx4 v[144:145], off
	s_waitcnt vmcnt(8)
	s_barrier
	s_waitcnt lgkmcnt(0)
	v_mfma_f32_16x16x32_bf16 v[128:131], v[148:151], v[196:199], v[128:131]
	v_mfma_f32_16x16x32_bf16 v[124:127], v[160:163], v[196:199], v[124:127]
	v_mfma_f32_16x16x32_bf16 v[112:115], v[148:151], v[204:207], v[112:115]
	v_mfma_f32_16x16x32_bf16 v[108:111], v[160:163], v[204:207], v[108:111]
	v_mfma_f32_16x16x32_bf16 v[96:99], v[148:151], v[212:215], v[96:99]
	v_mfma_f32_16x16x32_bf16 v[92:95], v[160:163], v[212:215], v[92:95]
	v_mfma_f32_16x16x32_bf16 v[80:83], v[148:151], v[220:223], v[80:83]
	v_mfma_f32_16x16x32_bf16 v[76:79], v[160:163], v[220:223], v[76:79]
	v_mfma_f32_16x16x32_bf16 v[128:131], v[156:159], v[200:203], v[128:131]
	v_mfma_f32_16x16x32_bf16 v[124:127], v[164:167], v[200:203], v[124:127]
	v_mfma_f32_16x16x32_bf16 v[112:115], v[156:159], v[208:211], v[112:115]
	v_mfma_f32_16x16x32_bf16 v[108:111], v[164:167], v[208:211], v[108:111]
	v_mfma_f32_16x16x32_bf16 v[96:99], v[156:159], v[216:219], v[96:99]
	v_mfma_f32_16x16x32_bf16 v[92:95], v[164:167], v[216:219], v[92:95]
	v_mfma_f32_16x16x32_bf16 v[80:83], v[156:159], v[224:227], v[80:83]
	v_mfma_f32_16x16x32_bf16 v[76:79], v[164:167], v[224:227], v[76:79]
	v_mfma_f32_16x16x32_bf16 v[120:123], v[168:171], v[196:199], v[120:123]
	v_mfma_f32_16x16x32_bf16 v[116:119], v[188:191], v[196:199], v[116:119]
	v_mfma_f32_16x16x32_bf16 v[104:107], v[168:171], v[204:207], v[104:107]
	v_mfma_f32_16x16x32_bf16 v[100:103], v[188:191], v[204:207], v[100:103]
	v_mfma_f32_16x16x32_bf16 v[88:91], v[168:171], v[212:215], v[88:91]
	v_mfma_f32_16x16x32_bf16 v[84:87], v[188:191], v[212:215], v[84:87]
	v_mfma_f32_16x16x32_bf16 v[72:75], v[168:171], v[220:223], v[72:75]
	v_mfma_f32_16x16x32_bf16 v[68:71], v[188:191], v[220:223], v[68:71]
	v_mfma_f32_16x16x32_bf16 v[120:123], v[184:187], v[200:203], v[120:123]
	v_mfma_f32_16x16x32_bf16 v[116:119], v[192:195], v[200:203], v[116:119]
	v_mfma_f32_16x16x32_bf16 v[104:107], v[184:187], v[208:211], v[104:107]
	v_mfma_f32_16x16x32_bf16 v[100:103], v[192:195], v[208:211], v[100:103]
	v_mfma_f32_16x16x32_bf16 v[88:91], v[184:187], v[216:219], v[88:91]
	v_mfma_f32_16x16x32_bf16 v[84:87], v[192:195], v[216:219], v[84:87]
	v_mfma_f32_16x16x32_bf16 v[72:75], v[184:187], v[224:227], v[72:75]
	v_mfma_f32_16x16x32_bf16 v[68:71], v[192:195], v[224:227], v[68:71]
	s_barrier
	s_add_i32 s55, s55, s24
	v_lshl_add_u64 v[144:145], s[40:41], 0, v[174:175]
	s_mov_b32 m0, s55
	ds_read_b128 v[196:199], v155 offset:16384
	ds_read_b128 v[200:203], v155 offset:17408
	ds_read_b128 v[204:207], v155 offset:18432
	ds_read_b128 v[208:211], v155 offset:19456
	ds_read_b128 v[212:215], v155 offset:20480
	ds_read_b128 v[216:219], v155 offset:21504
	ds_read_b128 v[220:223], v155 offset:22528
	ds_read_b128 v[224:227], v155 offset:23552
	global_load_lds_dwordx4 v[144:145], off
	s_add_i32 m0, s55, 0x2000
	s_add_u32 s56, s40, 0x80000
	v_lshl_add_u64 v[228:229], s[40:41], 0, v[132:133]
	s_addc_u32 s57, s41, 0
	s_add_i32 s55, s58, s24
	global_load_lds_dwordx4 v[228:229], off
	v_lshl_add_u64 v[230:231], s[56:57], 0, v[174:175]
	s_mov_b32 m0, s55
	v_lshl_add_u64 v[232:233], s[26:27], 0, v[134:135]
	global_load_lds_dwordx4 v[230:231], off
	v_lshl_add_u64 v[230:231], s[56:57], 0, v[132:133]
	s_add_i32 m0, s55, 0x2000
	s_nop 0
	global_load_lds_dwordx4 v[230:231], off
	v_lshl_add_u64 v[230:231], s[26:27], 0, v[136:137]
	s_mov_b32 m0, s25
	s_nop 0
	global_load_lds_dwordx4 v[230:231], off
	s_mov_b32 m0, s42
	s_nop 0
	global_load_lds_dwordx4 v[232:233], off
	s_waitcnt vmcnt(8)
	s_barrier
; #define PG8_STAGE(bufoff, gbase, voff) do { _Pragma("unroll") for (int _i = 0; _i < 2; ++_i) \
;         __builtin_amdgcn_global_load_lds((const unsigned*)((const char*)(gbase) + (voff)[_i]), (PG8_LAS unsigned*)(lds + (bufoff) + ldsw + _i * 8192), 16, 0, 0); } while (0)
; #define PG8_LDA(dst, b, h) do { _Pragma("unroll") for (int m = 0; m < 4; ++m) _Pragma("unroll") for (int k = 0; k < 2; ++k) dst[m][k] = *(const PG8_LAS bf16x8*)(lds + PG8_SA(b, h) + aoff + m * 2048 + k * 1024); } while (0)
; #define PG8_LDB(dst, b, h) do { _Pragma("unroll") for (int n = 0; n < 2; ++n) _Pragma("unroll") for (int k = 0; k < 2; ++k) dst[n][k] = *(const PG8_LAS bf16x8*)(lds + PG8_SB(b, h) + boff + n * 2048 + k * 1024); } while (0)
; #define PG8_MMA(ai, bj, At, Bt) do { __builtin_amdgcn_s_setprio(1); _Pragma("unroll") for (int m = 0; m < 4; ++m) _Pragma("unroll") for (int n = 0; n < 2; ++n) _Pragma("unroll") for (int k = 0; k < 2; ++k) \
;         acc[ai][bj][m][n] = __builtin_amdgcn_mfma_f32_16x16x32_bf16(Bt[n][k], At[m][k], acc[ai][bj][m][n], 0, 0, 0); __builtin_amdgcn_s_setprio(0); } while (0)
; #define PG8_WAIT_V(n) asm volatile("s_waitcnt vmcnt(" #n ")" ::: "memory")
; #define PG8_WAIT_L(n) asm volatile("s_waitcnt lgkmcnt(" #n ")" ::: "memory")
; #define PG8_BAR __builtin_amdgcn_s_barrier()
; #define PG8_SCHED __builtin_amdgcn_sched_barrier(0)
; template <class Epi, class Sched, bool ALIGN_EPI = false, bool SP2 = false>
; __device__ __forceinline__ void gemm_phase(PG8_LAS unsigned char* lds, const Gemm g, const Sched& S, const Epi& E) {
;     ...
;             PG8_WAIT_V(8); PG8_WAIT_L(0); PG8_BAR; PG8_MMA(1, 0, At, B0); PG8_MMA(1, 1, At, B1); PG8_BAR; PG8_SCHED;
;             PG8_LDB(B0, 1, 0); PG8_LDB(B1, 1, 1); PG8_SCHED; PG8_LDA(At, 1, 0); PG8_STAGE(PG8_SA(0, 1), a2 + hstep, voffA);
;             PG8_WAIT_V(8); PG8_WAIT_L(0); PG8_BAR; PG8_MMA(0, 0, At, B0); PG8_MMA(0, 1, At, B1); PG8_BAR; PG8_SCHED;
	s_waitcnt lgkmcnt(0)
	v_mfma_f32_16x16x32_bf16 v[64:67], v[148:151], v[196:199], v[64:67]
	v_mfma_f32_16x16x32_bf16 v[60:63], v[160:163], v[196:199], v[60:63]
	v_mfma_f32_16x16x32_bf16 v[52:55], v[148:151], v[204:207], v[52:55]
	v_mfma_f32_16x16x32_bf16 v[44:47], v[160:163], v[204:207], v[44:47]
	v_mfma_f32_16x16x32_bf16 v[36:39], v[148:151], v[212:215], v[36:39]
	v_mfma_f32_16x16x32_bf16 v[28:31], v[160:163], v[212:215], v[28:31]
	v_mfma_f32_16x16x32_bf16 v[20:23], v[148:151], v[220:223], v[20:23]
	v_mfma_f32_16x16x32_bf16 v[12:15], v[160:163], v[220:223], v[12:15]
	v_mfma_f32_16x16x32_bf16 v[64:67], v[156:159], v[200:203], v[64:67]
	v_mfma_f32_16x16x32_bf16 v[60:63], v[164:167], v[200:203], v[60:63]
	v_mfma_f32_16x16x32_bf16 v[52:55], v[156:159], v[208:211], v[52:55]
	v_mfma_f32_16x16x32_bf16 v[44:47], v[164:167], v[208:211], v[44:47]
	v_mfma_f32_16x16x32_bf16 v[36:39], v[156:159], v[216:219], v[36:39]
	v_mfma_f32_16x16x32_bf16 v[28:31], v[164:167], v[216:219], v[28:31]
	v_mfma_f32_16x16x32_bf16 v[20:23], v[156:159], v[224:227], v[20:23]
	v_mfma_f32_16x16x32_bf16 v[12:15], v[164:167], v[224:227], v[12:15]
	v_mfma_f32_16x16x32_bf16 v[56:59], v[168:171], v[196:199], v[56:59]
	v_mfma_f32_16x16x32_bf16 v[48:51], v[188:191], v[196:199], v[48:51]
	v_mfma_f32_16x16x32_bf16 v[40:43], v[168:171], v[204:207], v[40:43]
	v_mfma_f32_16x16x32_bf16 v[32:35], v[188:191], v[204:207], v[32:35]
	v_mfma_f32_16x16x32_bf16 v[24:27], v[168:171], v[212:215], v[24:27]
	v_mfma_f32_16x16x32_bf16 v[16:19], v[188:191], v[212:215], v[16:19]
	v_mfma_f32_16x16x32_bf16 v[8:11], v[168:171], v[220:223], v[8:11]
	v_mfma_f32_16x16x32_bf16 v[4:7], v[188:191], v[220:223], v[4:7]
	v_mfma_f32_16x16x32_bf16 v[56:59], v[184:187], v[200:203], v[56:59]
	v_mfma_f32_16x16x32_bf16 v[48:51], v[192:195], v[200:203], v[48:51]
	v_mfma_f32_16x16x32_bf16 v[40:43], v[184:187], v[208:211], v[40:43]
	v_mfma_f32_16x16x32_bf16 v[32:35], v[192:195], v[208:211], v[32:35]
	v_mfma_f32_16x16x32_bf16 v[24:27], v[184:187], v[216:219], v[24:27]
	v_mfma_f32_16x16x32_bf16 v[16:19], v[192:195], v[216:219], v[16:19]
	v_mfma_f32_16x16x32_bf16 v[8:11], v[184:187], v[224:227], v[8:11]
	v_mfma_f32_16x16x32_bf16 v[4:7], v[192:195], v[224:227], v[4:7]
	s_barrier
	s_add_i32 s55, 0, 0x18000
	v_add_u32_e32 v142, s55, v147
	s_add_i32 s56, 0, 0x1c000
	ds_read_b128 v[148:151], v142
	ds_read_b128 v[156:159], v142 offset:1024
	ds_read_b128 v[160:163], v142 offset:2048
	ds_read_b128 v[164:167], v142 offset:3072
	v_add_u32_e32 v142, s56, v147
	ds_read_b128 v[168:171], v142
	ds_read_b128 v[184:187], v142 offset:1024
	ds_read_b128 v[188:191], v142 offset:2048
	ds_read_b128 v[192:195], v142 offset:3072
	s_add_u32 s26, s26, 0x80000
	s_addc_u32 s27, s27, 0
	s_mov_b32 m0, s43
	v_lshl_add_u64 v[234:235], s[26:27], 0, v[136:137]
	ds_read_b128 v[196:199], v155 offset:32768
	ds_read_b128 v[200:203], v155 offset:33792
	ds_read_b128 v[204:207], v155 offset:34816
	ds_read_b128 v[208:211], v155 offset:35840
	ds_read_b128 v[212:215], v155 offset:36864
	ds_read_b128 v[216:219], v155 offset:37888
	ds_read_b128 v[220:223], v155 offset:38912
	ds_read_b128 v[224:227], v155 offset:39936
	global_load_lds_dwordx4 v[234:235], off
	v_lshl_add_u64 v[234:235], s[26:27], 0, v[134:135]
	s_mov_b32 m0, s44
	s_nop 0
	global_load_lds_dwordx4 v[234:235], off
	s_waitcnt vmcnt(8)
	s_barrier
	s_waitcnt lgkmcnt(0)
	v_mfma_f32_16x16x32_bf16 v[128:131], v[148:151], v[196:199], v[128:131]
	v_mfma_f32_16x16x32_bf16 v[124:127], v[160:163], v[196:199], v[124:127]
	v_mfma_f32_16x16x32_bf16 v[112:115], v[148:151], v[204:207], v[112:115]
	v_mfma_f32_16x16x32_bf16 v[108:111], v[160:163], v[204:207], v[108:111]
	v_mfma_f32_16x16x32_bf16 v[96:99], v[148:151], v[212:215], v[96:99]
	v_mfma_f32_16x16x32_bf16 v[92:95], v[160:163], v[212:215], v[92:95]
	v_mfma_f32_16x16x32_bf16 v[80:83], v[148:151], v[220:223], v[80:83]
	v_mfma_f32_16x16x32_bf16 v[76:79], v[160:163], v[220:223], v[76:79]
	v_mfma_f32_16x16x32_bf16 v[128:131], v[156:159], v[200:203], v[128:131]
	v_mfma_f32_16x16x32_bf16 v[124:127], v[164:167], v[200:203], v[124:127]
	v_mfma_f32_16x16x32_bf16 v[112:115], v[156:159], v[208:211], v[112:115]
	v_mfma_f32_16x16x32_bf16 v[108:111], v[164:167], v[208:211], v[108:111]
	v_mfma_f32_16x16x32_bf16 v[96:99], v[156:159], v[216:219], v[96:99]
	v_mfma_f32_16x16x32_bf16 v[92:95], v[164:167], v[216:219], v[92:95]
	v_mfma_f32_16x16x32_bf16 v[80:83], v[156:159], v[224:227], v[80:83]
	v_mfma_f32_16x16x32_bf16 v[76:79], v[164:167], v[224:227], v[76:79]
	v_mfma_f32_16x16x32_bf16 v[120:123], v[168:171], v[196:199], v[120:123]
	v_mfma_f32_16x16x32_bf16 v[116:119], v[188:191], v[196:199], v[116:119]
	v_mfma_f32_16x16x32_bf16 v[104:107], v[168:171], v[204:207], v[104:107]
	v_mfma_f32_16x16x32_bf16 v[100:103], v[188:191], v[204:207], v[100:103]
	v_mfma_f32_16x16x32_bf16 v[88:91], v[168:171], v[212:215], v[88:91]
	v_mfma_f32_16x16x32_bf16 v[84:87], v[188:191], v[212:215], v[84:87]
	v_mfma_f32_16x16x32_bf16 v[72:75], v[168:171], v[220:223], v[72:75]
	v_mfma_f32_16x16x32_bf16 v[68:71], v[188:191], v[220:223], v[68:71]
	v_mfma_f32_16x16x32_bf16 v[120:123], v[184:187], v[200:203], v[120:123]
	v_mfma_f32_16x16x32_bf16 v[116:119], v[192:195], v[200:203], v[116:119]
	v_mfma_f32_16x16x32_bf16 v[104:107], v[184:187], v[208:211], v[104:107]
	v_mfma_f32_16x16x32_bf16 v[100:103], v[192:195], v[208:211], v[100:103]
	v_mfma_f32_16x16x32_bf16 v[88:91], v[184:187], v[216:219], v[88:91]
	v_mfma_f32_16x16x32_bf16 v[84:87], v[192:195], v[216:219], v[84:87]
	v_mfma_f32_16x16x32_bf16 v[72:75], v[184:187], v[224:227], v[72:75]
	v_mfma_f32_16x16x32_bf16 v[68:71], v[192:195], v[224:227], v[68:71]
	s_barrier
; #define PG8_STAGE(bufoff, gbase, voff) do { _Pragma("unroll") for (int _i = 0; _i < 2; ++_i) \
;         __builtin_amdgcn_global_load_lds((const unsigned*)((const char*)(gbase) + (voff)[_i]), (PG8_LAS unsigned*)(lds + (bufoff) + ldsw + _i * 8192), 16, 0, 0); } while (0)
; #define PG8_LDA(dst, b, h) do { _Pragma("unroll") for (int m = 0; m < 4; ++m) _Pragma("unroll") for (int k = 0; k < 2; ++k) dst[m][k] = *(const PG8_LAS bf16x8*)(lds + PG8_SA(b, h) + aoff + m * 2048 + k * 1024); } while (0)
; #define PG8_MMA(ai, bj, At, Bt) do { __builtin_amdgcn_s_setprio(1); _Pragma("unroll") for (int m = 0; m < 4; ++m) _Pragma("unroll") for (int n = 0; n < 2; ++n) _Pragma("unroll") for (int k = 0; k < 2; ++k) \
;         acc[ai][bj][m][n] = __builtin_amdgcn_mfma_f32_16x16x32_bf16(Bt[n][k], At[m][k], acc[ai][bj][m][n], 0, 0, 0); __builtin_amdgcn_s_setprio(0); } while (0)
; #define PG8_WAIT_V(n) asm volatile("s_waitcnt vmcnt(" #n ")" ::: "memory")
; #define PG8_WAIT_L(n) asm volatile("s_waitcnt lgkmcnt(" #n ")" ::: "memory")
; #define PG8_BAR __builtin_amdgcn_s_barrier()
; #define PG8_SCHED __builtin_amdgcn_sched_barrier(0)
; template <class Epi, class Sched, bool ALIGN_EPI = false, bool SP2 = false>
; __device__ __forceinline__ void gemm_phase(PG8_LAS unsigned char* lds, const Gemm g, const Sched& S, const Epi& E) {
;     ...
;         for (int t = 0; t < nt; t += 2) {
;             const bool last = (t == nt - 2);
;     ...
;             PG8_LDA(At, 1, 1); PG8_STAGE(PG8_SB(1, 0), b3, voffB); PG8_STAGE(PG8_SB(1, 1), b3 + hstep, voffB); PG8_STAGE(PG8_SA(1, 0), a3, voffA);
;             PG8_WAIT_V(8); PG8_WAIT_L(0); PG8_BAR; PG8_MMA(1, 0, At, B0); PG8_MMA(1, 1, At, B1); PG8_BAR; PG8_SCHED;
	s_add_i32 s26, s55, s24
	v_lshl_add_u64 v[144:145], v[144:145], 0, s[10:11]
	s_mov_b32 m0, s26
	ds_read_b128 v[196:199], v155 offset:49152
	ds_read_b128 v[200:203], v155 offset:50176
	ds_read_b128 v[204:207], v155 offset:51200
	ds_read_b128 v[208:211], v155 offset:52224
	ds_read_b128 v[212:215], v155 offset:53248
	ds_read_b128 v[216:219], v155 offset:54272
	ds_read_b128 v[220:223], v155 offset:55296
	ds_read_b128 v[224:227], v155 offset:56320
	global_load_lds_dwordx4 v[144:145], off
	s_add_i32 m0, s26, 0x2000
	s_add_u32 s26, s40, 0x80080
	v_lshl_add_u64 v[144:145], v[228:229], 0, s[10:11]
	s_addc_u32 s27, s41, 0
	s_add_i32 s40, s56, s24
	global_load_lds_dwordx4 v[144:145], off
	v_lshl_add_u64 v[144:145], s[26:27], 0, v[174:175]
	s_mov_b32 m0, s40
	s_nop 0
	global_load_lds_dwordx4 v[144:145], off
	v_lshl_add_u64 v[144:145], s[26:27], 0, v[132:133]
	s_add_i32 m0, s40, 0x2000
	s_nop 0
	global_load_lds_dwordx4 v[144:145], off
	v_lshl_add_u64 v[144:145], v[230:231], 0, s[10:11]
	s_mov_b32 m0, s20
	s_nop 0
	global_load_lds_dwordx4 v[144:145], off
	v_lshl_add_u64 v[144:145], v[232:233], 0, s[10:11]
	s_mov_b32 m0, s45
	s_nop 0
	global_load_lds_dwordx4 v[144:145], off
	s_waitcnt vmcnt(8)
	s_barrier
	s_waitcnt lgkmcnt(0)
	v_mfma_f32_16x16x32_bf16 v[64:67], v[148:151], v[196:199], v[64:67]
	v_mfma_f32_16x16x32_bf16 v[60:63], v[160:163], v[196:199], v[60:63]
	v_mfma_f32_16x16x32_bf16 v[52:55], v[148:151], v[204:207], v[52:55]
	v_mfma_f32_16x16x32_bf16 v[44:47], v[160:163], v[204:207], v[44:47]
	v_mfma_f32_16x16x32_bf16 v[36:39], v[148:151], v[212:215], v[36:39]
	v_mfma_f32_16x16x32_bf16 v[28:31], v[160:163], v[212:215], v[28:31]
	v_mfma_f32_16x16x32_bf16 v[20:23], v[148:151], v[220:223], v[20:23]
	v_mfma_f32_16x16x32_bf16 v[12:15], v[160:163], v[220:223], v[12:15]
	v_mfma_f32_16x16x32_bf16 v[64:67], v[156:159], v[200:203], v[64:67]
	v_mfma_f32_16x16x32_bf16 v[60:63], v[164:167], v[200:203], v[60:63]
	v_mfma_f32_16x16x32_bf16 v[52:55], v[156:159], v[208:211], v[52:55]
	v_mfma_f32_16x16x32_bf16 v[44:47], v[164:167], v[208:211], v[44:47]
	v_mfma_f32_16x16x32_bf16 v[36:39], v[156:159], v[216:219], v[36:39]
	v_mfma_f32_16x16x32_bf16 v[28:31], v[164:167], v[216:219], v[28:31]
	v_mfma_f32_16x16x32_bf16 v[20:23], v[156:159], v[224:227], v[20:23]
	v_mfma_f32_16x16x32_bf16 v[12:15], v[164:167], v[224:227], v[12:15]
	v_mfma_f32_16x16x32_bf16 v[56:59], v[168:171], v[196:199], v[56:59]
	v_mfma_f32_16x16x32_bf16 v[48:51], v[188:191], v[196:199], v[48:51]
	v_mfma_f32_16x16x32_bf16 v[40:43], v[168:171], v[204:207], v[40:43]
	v_mfma_f32_16x16x32_bf16 v[32:35], v[188:191], v[204:207], v[32:35]
	v_mfma_f32_16x16x32_bf16 v[24:27], v[168:171], v[212:215], v[24:27]
	v_mfma_f32_16x16x32_bf16 v[16:19], v[188:191], v[212:215], v[16:19]
	v_mfma_f32_16x16x32_bf16 v[8:11], v[168:171], v[220:223], v[8:11]
	v_mfma_f32_16x16x32_bf16 v[4:7], v[188:191], v[220:223], v[4:7]
	v_mfma_f32_16x16x32_bf16 v[56:59], v[184:187], v[200:203], v[56:59]
	v_mfma_f32_16x16x32_bf16 v[48:51], v[192:195], v[200:203], v[48:51]
	v_mfma_f32_16x16x32_bf16 v[40:43], v[184:187], v[208:211], v[40:43]
	v_mfma_f32_16x16x32_bf16 v[32:35], v[192:195], v[208:211], v[32:35]
	v_mfma_f32_16x16x32_bf16 v[24:27], v[184:187], v[216:219], v[24:27]
	v_mfma_f32_16x16x32_bf16 v[16:19], v[192:195], v[216:219], v[16:19]
	v_mfma_f32_16x16x32_bf16 v[8:11], v[184:187], v[224:227], v[8:11]
	v_mfma_f32_16x16x32_bf16 v[4:7], v[192:195], v[224:227], v[4:7]
	s_barrier
	s_add_i32 s54, s54, 2
	s_add_u32 s52, s52, 0x100
	s_addc_u32 s53, s53, 0
	s_add_u32 s38, s38, 0x100
	s_addc_u32 s39, s39, 0
	s_cmp_gt_u32 s54, 29
	s_cbranch_scc0 .LBB0_86
	s_and_b64 vcc, exec, s[16:17]
	s_cbranch_vccz .LBB0_89
	s_barrier

; #define PG8_STAGE(bufoff, gbase, voff) do { _Pragma("unroll") for (int _i = 0; _i < 2; ++_i) \
;         __builtin_amdgcn_global_load_lds((const unsigned*)((const char*)(gbase) + (voff)[_i]), (PG8_LAS unsigned*)(lds + (bufoff) + ldsw + _i * 8192), 16, 0, 0); } while (0)
; #define PG8_LDA(dst, b, h) do { _Pragma("unroll") for (int m = 0; m < 4; ++m) _Pragma("unroll") for (int k = 0; k < 2; ++k) dst[m][k] = *(const PG8_LAS bf16x8*)(lds + PG8_SA(b, h) + aoff + m * 2048 + k * 1024); } while (0)
; #define PG8_LDB(dst, b, h) do { _Pragma("unroll") for (int n = 0; n < 2; ++n) _Pragma("unroll") for (int k = 0; k < 2; ++k) dst[n][k] = *(const PG8_LAS bf16x8*)(lds + PG8_SB(b, h) + boff + n * 2048 + k * 1024); } while (0)
; #define PG8_MMA(ai, bj, At, Bt) do { __builtin_amdgcn_s_setprio(1); _Pragma("unroll") for (int m = 0; m < 4; ++m) _Pragma("unroll") for (int n = 0; n < 2; ++n) _Pragma("unroll") for (int k = 0; k < 2; ++k) \
;         acc[ai][bj][m][n] = __builtin_amdgcn_mfma_f32_16x16x32_bf16(Bt[n][k], At[m][k], acc[ai][bj][m][n], 0, 0, 0); __builtin_amdgcn_s_setprio(0); } while (0)
; #define PG8_WAIT_V(n) asm volatile("s_waitcnt vmcnt(" #n ")" ::: "memory")
; #define PG8_WAIT_L(n) asm volatile("s_waitcnt lgkmcnt(" #n ")" ::: "memory")
; #define PG8_BAR __builtin_amdgcn_s_barrier()
; #define PG8_SCHED __builtin_amdgcn_sched_barrier(0)
; template <class Epi, class Sched, bool ALIGN_EPI = false, bool SP2 = false>
; __device__ __forceinline__ void gemm_phase(PG8_LAS unsigned char* lds, const Gemm g, const Sched& S, const Epi& E) {
;     ...
;             PG8_LDB(B0, 0, 0); PG8_LDB(B1, 0, 1); PG8_SCHED; PG8_LDA(At, 0, 0); PG8_STAGE(PG8_SA(1, 1), a1 + hstep, voffA);
;             PG8_WAIT_V(8); PG8_WAIT_L(0); PG8_BAR; PG8_MMA(0, 0, At, B0); PG8_MMA(0, 1, At, B1); PG8_BAR; PG8_SCHED;
;             PG8_LDA(At, 0, 1); PG8_STAGE(PG8_SB(0, 0), b2, voffB); PG8_STAGE(PG8_SB(0, 1), b2 + hstep, voffB); PG8_STAGE(PG8_SA(0, 0), a2, voffA);
;             PG8_WAIT_V(8); PG8_WAIT_L(0); PG8_BAR; PG8_MMA(1, 0, At, B0); PG8_MMA(1, 1, At, B1); PG8_BAR; PG8_SCHED;
.Lprio_done_407:
.LBB0_407:
	s_add_u32 s14, s0, 0xfff80080
	s_addc_u32 s15, s1, -1
	s_add_i32 s59, 0, 0x10000
	s_cmp_eq_u32 s58, 28
	s_cselect_b32 s17, s23, s15
	s_cselect_b32 s16, s24, s14
	s_cselect_b32 s15, s25, s57
	s_cselect_b32 s14, s49, s51
	s_add_i32 s62, 0, 0x14000
	v_add_u32_e32 v154, s59, v171
	v_add_u32_e32 v185, s62, v171
	ds_read_b128 v[100:103], v154
	ds_read_b128 v[104:107], v154 offset:1024
	ds_read_b128 v[140:143], v154 offset:2048
	ds_read_b128 v[154:157], v154 offset:3072
	ds_read_b128 v[158:161], v185
	ds_read_b128 v[162:165], v185 offset:1024
	ds_read_b128 v[166:169], v185 offset:2048
	ds_read_b128 v[186:189], v185 offset:3072
	v_lshl_add_u64 v[222:223], s[0:1], 0, v[152:153]
	s_add_i32 m0, s29, 0xc000
	ds_read_b128 v[190:193], v184
	ds_read_b128 v[194:197], v184 offset:1024
	ds_read_b128 v[198:201], v184 offset:2048
	ds_read_b128 v[202:205], v184 offset:3072
	ds_read_b128 v[206:209], v184 offset:4096
	ds_read_b128 v[210:213], v184 offset:5120
	ds_read_b128 v[214:217], v184 offset:6144
	ds_read_b128 v[218:221], v184 offset:7168
	global_load_lds_dwordx4 v[222:223], off
	v_lshl_add_u64 v[222:223], s[0:1], 0, v[150:151]
	s_add_i32 m0, s29, 0xe000
	s_nop 0
	global_load_lds_dwordx4 v[222:223], off
	s_waitcnt vmcnt(8)
	s_barrier
	s_waitcnt lgkmcnt(0)
	v_mfma_f32_16x16x32_bf16 v[136:139], v[100:103], v[190:193], v[136:139]
	v_mfma_f32_16x16x32_bf16 v[132:135], v[140:143], v[190:193], v[132:135]
	v_mfma_f32_16x16x32_bf16 v[128:131], v[100:103], v[198:201], v[128:131]
	v_mfma_f32_16x16x32_bf16 v[124:127], v[140:143], v[198:201], v[124:127]
	v_mfma_f32_16x16x32_bf16 v[120:123], v[100:103], v[206:209], v[120:123]
	v_mfma_f32_16x16x32_bf16 v[116:119], v[140:143], v[206:209], v[116:119]
	v_mfma_f32_16x16x32_bf16 v[112:115], v[100:103], v[214:217], v[112:115]
	v_mfma_f32_16x16x32_bf16 v[108:111], v[140:143], v[214:217], v[108:111]
	v_mfma_f32_16x16x32_bf16 v[136:139], v[104:107], v[194:197], v[136:139]
	v_mfma_f32_16x16x32_bf16 v[132:135], v[154:157], v[194:197], v[132:135]
	v_mfma_f32_16x16x32_bf16 v[128:131], v[104:107], v[202:205], v[128:131]
	v_mfma_f32_16x16x32_bf16 v[124:127], v[154:157], v[202:205], v[124:127]
	v_mfma_f32_16x16x32_bf16 v[120:123], v[104:107], v[210:213], v[120:123]
	v_mfma_f32_16x16x32_bf16 v[116:119], v[154:157], v[210:213], v[116:119]
	v_mfma_f32_16x16x32_bf16 v[112:115], v[104:107], v[218:221], v[112:115]
	v_mfma_f32_16x16x32_bf16 v[108:111], v[154:157], v[218:221], v[108:111]
	v_mfma_f32_16x16x32_bf16 v[64:67], v[158:161], v[190:193], v[64:67]
	v_mfma_f32_16x16x32_bf16 v[60:63], v[166:169], v[190:193], v[60:63]
	v_mfma_f32_16x16x32_bf16 v[56:59], v[158:161], v[198:201], v[56:59]
	v_mfma_f32_16x16x32_bf16 v[52:55], v[166:169], v[198:201], v[52:55]
	v_mfma_f32_16x16x32_bf16 v[48:51], v[158:161], v[206:209], v[48:51]
	v_mfma_f32_16x16x32_bf16 v[44:47], v[166:169], v[206:209], v[44:47]
	v_mfma_f32_16x16x32_bf16 v[40:43], v[158:161], v[214:217], v[40:43]
	v_mfma_f32_16x16x32_bf16 v[36:39], v[166:169], v[214:217], v[36:39]
	v_mfma_f32_16x16x32_bf16 v[64:67], v[162:165], v[194:197], v[64:67]
	v_mfma_f32_16x16x32_bf16 v[60:63], v[186:189], v[194:197], v[60:63]
	v_mfma_f32_16x16x32_bf16 v[56:59], v[162:165], v[202:205], v[56:59]
	v_mfma_f32_16x16x32_bf16 v[52:55], v[186:189], v[202:205], v[52:55]
	v_mfma_f32_16x16x32_bf16 v[48:51], v[162:165], v[210:213], v[48:51]
	v_mfma_f32_16x16x32_bf16 v[44:47], v[186:189], v[210:213], v[44:47]
	v_mfma_f32_16x16x32_bf16 v[40:43], v[162:165], v[218:221], v[40:43]
	v_mfma_f32_16x16x32_bf16 v[36:39], v[186:189], v[218:221], v[36:39]
	s_barrier
	s_add_i32 s59, s59, s28
	v_lshl_add_u64 v[222:223], s[14:15], 0, v[174:175]
	s_mov_b32 m0, s59
	ds_read_b128 v[190:193], v184 offset:16384
	ds_read_b128 v[194:197], v184 offset:17408
	ds_read_b128 v[198:201], v184 offset:18432
	ds_read_b128 v[202:205], v184 offset:19456
	ds_read_b128 v[206:209], v184 offset:20480
	ds_read_b128 v[210:213], v184 offset:21504
	ds_read_b128 v[214:217], v184 offset:22528
	ds_read_b128 v[218:221], v184 offset:23552
	global_load_lds_dwordx4 v[222:223], off
	s_add_i32 m0, s59, 0x2000
	s_add_u32 s60, s14, 0x80000
	v_lshl_add_u64 v[224:225], s[14:15], 0, v[144:145]
	s_addc_u32 s61, s15, 0
	s_add_i32 s59, s62, s28
	global_load_lds_dwordx4 v[224:225], off
	v_lshl_add_u64 v[226:227], s[60:61], 0, v[174:175]
	s_mov_b32 m0, s59
	v_lshl_add_u64 v[228:229], s[16:17], 0, v[146:147]
	global_load_lds_dwordx4 v[226:227], off
	v_lshl_add_u64 v[226:227], s[60:61], 0, v[144:145]
	s_add_i32 m0, s59, 0x2000
	s_nop 0
	global_load_lds_dwordx4 v[226:227], off
	v_lshl_add_u64 v[226:227], s[16:17], 0, v[148:149]
	s_mov_b32 m0, s29
	s_nop 0
	global_load_lds_dwordx4 v[226:227], off
	s_mov_b32 m0, s30
	s_nop 0
	global_load_lds_dwordx4 v[228:229], off
	s_waitcnt vmcnt(8)
	s_barrier
; #define PG8_STAGE(bufoff, gbase, voff) do { _Pragma("unroll") for (int _i = 0; _i < 2; ++_i) \
;         __builtin_amdgcn_global_load_lds((const unsigned*)((const char*)(gbase) + (voff)[_i]), (PG8_LAS unsigned*)(lds + (bufoff) + ldsw + _i * 8192), 16, 0, 0); } while (0)
; #define PG8_LDA(dst, b, h) do { _Pragma("unroll") for (int m = 0; m < 4; ++m) _Pragma("unroll") for (int k = 0; k < 2; ++k) dst[m][k] = *(const PG8_LAS bf16x8*)(lds + PG8_SA(b, h) + aoff + m * 2048 + k * 1024); } while (0)
; #define PG8_LDB(dst, b, h) do { _Pragma("unroll") for (int n = 0; n < 2; ++n) _Pragma("unroll") for (int k = 0; k < 2; ++k) dst[n][k] = *(const PG8_LAS bf16x8*)(lds + PG8_SB(b, h) + boff + n * 2048 + k * 1024); } while (0)
; #define PG8_MMA(ai, bj, At, Bt) do { __builtin_amdgcn_s_setprio(1); _Pragma("unroll") for (int m = 0; m < 4; ++m) _Pragma("unroll") for (int n = 0; n < 2; ++n) _Pragma("unroll") for (int k = 0; k < 2; ++k) \
;         acc[ai][bj][m][n] = __builtin_amdgcn_mfma_f32_16x16x32_bf16(Bt[n][k], At[m][k], acc[ai][bj][m][n], 0, 0, 0); __builtin_amdgcn_s_setprio(0); } while (0)
; #define PG8_WAIT_V(n) asm volatile("s_waitcnt vmcnt(" #n ")" ::: "memory")
; #define PG8_WAIT_L(n) asm volatile("s_waitcnt lgkmcnt(" #n ")" ::: "memory")
; #define PG8_BAR __builtin_amdgcn_s_barrier()
; #define PG8_SCHED __builtin_amdgcn_sched_barrier(0)
; template <class Epi, class Sched, bool ALIGN_EPI = false, bool SP2 = false>
; __device__ __forceinline__ void gemm_phase(PG8_LAS unsigned char* lds, const Gemm g, const Sched& S, const Epi& E) {
;     ...
;             PG8_WAIT_V(8); PG8_WAIT_L(0); PG8_BAR; PG8_MMA(1, 0, At, B0); PG8_MMA(1, 1, At, B1); PG8_BAR; PG8_SCHED;
;             PG8_LDB(B0, 1, 0); PG8_LDB(B1, 1, 1); PG8_SCHED; PG8_LDA(At, 1, 0); PG8_STAGE(PG8_SA(0, 1), a2 + hstep, voffA);
;             PG8_WAIT_V(8); PG8_WAIT_L(0); PG8_BAR; PG8_MMA(0, 0, At, B0); PG8_MMA(0, 1, At, B1); PG8_BAR; PG8_SCHED;
	s_waitcnt lgkmcnt(0)
	v_mfma_f32_16x16x32_bf16 v[96:99], v[100:103], v[190:193], v[96:99]
	v_mfma_f32_16x16x32_bf16 v[92:95], v[140:143], v[190:193], v[92:95]
	v_mfma_f32_16x16x32_bf16 v[88:91], v[100:103], v[198:201], v[88:91]
	v_mfma_f32_16x16x32_bf16 v[84:87], v[140:143], v[198:201], v[84:87]
	v_mfma_f32_16x16x32_bf16 v[80:83], v[100:103], v[206:209], v[80:83]
	v_mfma_f32_16x16x32_bf16 v[76:79], v[140:143], v[206:209], v[76:79]
	v_mfma_f32_16x16x32_bf16 v[72:75], v[100:103], v[214:217], v[72:75]
	v_mfma_f32_16x16x32_bf16 v[68:71], v[140:143], v[214:217], v[68:71]
	v_mfma_f32_16x16x32_bf16 v[96:99], v[104:107], v[194:197], v[96:99]
	v_mfma_f32_16x16x32_bf16 v[92:95], v[154:157], v[194:197], v[92:95]
	v_mfma_f32_16x16x32_bf16 v[88:91], v[104:107], v[202:205], v[88:91]
	v_mfma_f32_16x16x32_bf16 v[84:87], v[154:157], v[202:205], v[84:87]
	v_mfma_f32_16x16x32_bf16 v[80:83], v[104:107], v[210:213], v[80:83]
	v_mfma_f32_16x16x32_bf16 v[76:79], v[154:157], v[210:213], v[76:79]
	v_mfma_f32_16x16x32_bf16 v[72:75], v[104:107], v[218:221], v[72:75]
	v_mfma_f32_16x16x32_bf16 v[68:71], v[154:157], v[218:221], v[68:71]
	v_mfma_f32_16x16x32_bf16 v[32:35], v[158:161], v[190:193], v[32:35]
	v_mfma_f32_16x16x32_bf16 v[28:31], v[166:169], v[190:193], v[28:31]
	v_mfma_f32_16x16x32_bf16 v[24:27], v[158:161], v[198:201], v[24:27]
	v_mfma_f32_16x16x32_bf16 v[20:23], v[166:169], v[198:201], v[20:23]
	v_mfma_f32_16x16x32_bf16 v[16:19], v[158:161], v[206:209], v[16:19]
	v_mfma_f32_16x16x32_bf16 v[12:15], v[166:169], v[206:209], v[12:15]
	v_mfma_f32_16x16x32_bf16 v[8:11], v[158:161], v[214:217], v[8:11]
	v_mfma_f32_16x16x32_bf16 v[4:7], v[166:169], v[214:217], v[4:7]
	v_mfma_f32_16x16x32_bf16 v[32:35], v[162:165], v[194:197], v[32:35]
	v_mfma_f32_16x16x32_bf16 v[28:31], v[186:189], v[194:197], v[28:31]
	v_mfma_f32_16x16x32_bf16 v[24:27], v[162:165], v[202:205], v[24:27]
	v_mfma_f32_16x16x32_bf16 v[20:23], v[186:189], v[202:205], v[20:23]
	v_mfma_f32_16x16x32_bf16 v[16:19], v[162:165], v[210:213], v[16:19]
	v_mfma_f32_16x16x32_bf16 v[12:15], v[186:189], v[210:213], v[12:15]
	v_mfma_f32_16x16x32_bf16 v[8:11], v[162:165], v[218:221], v[8:11]
	v_mfma_f32_16x16x32_bf16 v[4:7], v[186:189], v[218:221], v[4:7]
	s_barrier
	s_add_i32 s59, 0, 0x18000
	s_add_i32 s60, 0, 0x1c000
	v_add_u32_e32 v154, s59, v171
	v_add_u32_e32 v185, s60, v171
	ds_read_b128 v[100:103], v154
	ds_read_b128 v[104:107], v154 offset:1024
	ds_read_b128 v[140:143], v154 offset:2048
	ds_read_b128 v[154:157], v154 offset:3072
	ds_read_b128 v[158:161], v185
	ds_read_b128 v[162:165], v185 offset:1024
	ds_read_b128 v[166:169], v185 offset:2048
	ds_read_b128 v[186:189], v185 offset:3072
	s_add_u32 s16, s16, 0x80000
	s_addc_u32 s17, s17, 0
	s_mov_b32 m0, s31
	v_lshl_add_u64 v[230:231], s[16:17], 0, v[148:149]
	ds_read_b128 v[190:193], v184 offset:32768
	ds_read_b128 v[194:197], v184 offset:33792
	ds_read_b128 v[198:201], v184 offset:34816
	ds_read_b128 v[202:205], v184 offset:35840
	ds_read_b128 v[206:209], v184 offset:36864
	ds_read_b128 v[210:213], v184 offset:37888
	ds_read_b128 v[214:217], v184 offset:38912
	ds_read_b128 v[218:221], v184 offset:39936
	global_load_lds_dwordx4 v[230:231], off
	v_lshl_add_u64 v[230:231], s[16:17], 0, v[146:147]
	s_mov_b32 m0, s34
	s_nop 0
	global_load_lds_dwordx4 v[230:231], off
	s_waitcnt vmcnt(8)
	s_barrier
	s_waitcnt lgkmcnt(0)
	v_mfma_f32_16x16x32_bf16 v[136:139], v[100:103], v[190:193], v[136:139]
	v_mfma_f32_16x16x32_bf16 v[132:135], v[140:143], v[190:193], v[132:135]
	v_mfma_f32_16x16x32_bf16 v[128:131], v[100:103], v[198:201], v[128:131]
	v_mfma_f32_16x16x32_bf16 v[124:127], v[140:143], v[198:201], v[124:127]
	v_mfma_f32_16x16x32_bf16 v[120:123], v[100:103], v[206:209], v[120:123]
	v_mfma_f32_16x16x32_bf16 v[116:119], v[140:143], v[206:209], v[116:119]
	v_mfma_f32_16x16x32_bf16 v[112:115], v[100:103], v[214:217], v[112:115]
	v_mfma_f32_16x16x32_bf16 v[108:111], v[140:143], v[214:217], v[108:111]
	v_mfma_f32_16x16x32_bf16 v[136:139], v[104:107], v[194:197], v[136:139]
	v_mfma_f32_16x16x32_bf16 v[132:135], v[154:157], v[194:197], v[132:135]
	v_mfma_f32_16x16x32_bf16 v[128:131], v[104:107], v[202:205], v[128:131]
	v_mfma_f32_16x16x32_bf16 v[124:127], v[154:157], v[202:205], v[124:127]
	v_mfma_f32_16x16x32_bf16 v[120:123], v[104:107], v[210:213], v[120:123]
	v_mfma_f32_16x16x32_bf16 v[116:119], v[154:157], v[210:213], v[116:119]
	v_mfma_f32_16x16x32_bf16 v[112:115], v[104:107], v[218:221], v[112:115]
	v_mfma_f32_16x16x32_bf16 v[108:111], v[154:157], v[218:221], v[108:111]
	v_mfma_f32_16x16x32_bf16 v[64:67], v[158:161], v[190:193], v[64:67]
	v_mfma_f32_16x16x32_bf16 v[60:63], v[166:169], v[190:193], v[60:63]
	v_mfma_f32_16x16x32_bf16 v[56:59], v[158:161], v[198:201], v[56:59]
	v_mfma_f32_16x16x32_bf16 v[52:55], v[166:169], v[198:201], v[52:55]
	v_mfma_f32_16x16x32_bf16 v[48:51], v[158:161], v[206:209], v[48:51]
	v_mfma_f32_16x16x32_bf16 v[44:47], v[166:169], v[206:209], v[44:47]
	v_mfma_f32_16x16x32_bf16 v[40:43], v[158:161], v[214:217], v[40:43]
	v_mfma_f32_16x16x32_bf16 v[36:39], v[166:169], v[214:217], v[36:39]
	v_mfma_f32_16x16x32_bf16 v[64:67], v[162:165], v[194:197], v[64:67]
	v_mfma_f32_16x16x32_bf16 v[60:63], v[186:189], v[194:197], v[60:63]
	v_mfma_f32_16x16x32_bf16 v[56:59], v[162:165], v[202:205], v[56:59]
	v_mfma_f32_16x16x32_bf16 v[52:55], v[186:189], v[202:205], v[52:55]
	v_mfma_f32_16x16x32_bf16 v[48:51], v[162:165], v[210:213], v[48:51]
	v_mfma_f32_16x16x32_bf16 v[44:47], v[186:189], v[210:213], v[44:47]
	v_mfma_f32_16x16x32_bf16 v[40:43], v[162:165], v[218:221], v[40:43]
	v_mfma_f32_16x16x32_bf16 v[36:39], v[186:189], v[218:221], v[36:39]
	s_barrier
; #define PG8_STAGE(bufoff, gbase, voff) do { _Pragma("unroll") for (int _i = 0; _i < 2; ++_i) \
;         __builtin_amdgcn_global_load_lds((const unsigned*)((const char*)(gbase) + (voff)[_i]), (PG8_LAS unsigned*)(lds + (bufoff) + ldsw + _i * 8192), 16, 0, 0); } while (0)
; #define PG8_LDA(dst, b, h) do { _Pragma("unroll") for (int m = 0; m < 4; ++m) _Pragma("unroll") for (int k = 0; k < 2; ++k) dst[m][k] = *(const PG8_LAS bf16x8*)(lds + PG8_SA(b, h) + aoff + m * 2048 + k * 1024); } while (0)
; #define PG8_MMA(ai, bj, At, Bt) do { __builtin_amdgcn_s_setprio(1); _Pragma("unroll") for (int m = 0; m < 4; ++m) _Pragma("unroll") for (int n = 0; n < 2; ++n) _Pragma("unroll") for (int k = 0; k < 2; ++k) \
;         acc[ai][bj][m][n] = __builtin_amdgcn_mfma_f32_16x16x32_bf16(Bt[n][k], At[m][k], acc[ai][bj][m][n], 0, 0, 0); __builtin_amdgcn_s_setprio(0); } while (0)
; #define PG8_WAIT_V(n) asm volatile("s_waitcnt vmcnt(" #n ")" ::: "memory")
; #define PG8_WAIT_L(n) asm volatile("s_waitcnt lgkmcnt(" #n ")" ::: "memory")
; #define PG8_BAR __builtin_amdgcn_s_barrier()
; #define PG8_SCHED __builtin_amdgcn_sched_barrier(0)
; template <class Epi, class Sched, bool ALIGN_EPI = false, bool SP2 = false>
; __device__ __forceinline__ void gemm_phase(PG8_LAS unsigned char* lds, const Gemm g, const Sched& S, const Epi& E) {
;     ...
;         for (int t = 0; t < nt; t += 2) {
;             const bool last = (t == nt - 2);
;     ...
;             PG8_LDA(At, 1, 1); PG8_STAGE(PG8_SB(1, 0), b3, voffB); PG8_STAGE(PG8_SB(1, 1), b3 + hstep, voffB); PG8_STAGE(PG8_SA(1, 0), a3, voffA);
;             PG8_WAIT_V(8); PG8_WAIT_L(0); PG8_BAR; PG8_MMA(1, 0, At, B0); PG8_MMA(1, 1, At, B1); PG8_BAR; PG8_SCHED;
	s_add_i32 s16, s59, s28
	v_lshl_add_u64 v[222:223], v[222:223], 0, s[10:11]
	s_mov_b32 m0, s16
	ds_read_b128 v[190:193], v184 offset:49152
	ds_read_b128 v[194:197], v184 offset:50176
	ds_read_b128 v[198:201], v184 offset:51200
	ds_read_b128 v[202:205], v184 offset:52224
	ds_read_b128 v[206:209], v184 offset:53248
	ds_read_b128 v[210:213], v184 offset:54272
	ds_read_b128 v[214:217], v184 offset:55296
	ds_read_b128 v[218:221], v184 offset:56320
	global_load_lds_dwordx4 v[222:223], off
	s_add_i32 m0, s16, 0x2000
	s_add_u32 s14, s14, 0x80080
	v_lshl_add_u64 v[222:223], v[224:225], 0, s[10:11]
	s_addc_u32 s15, s15, 0
	s_add_i32 s16, s60, s28
	global_load_lds_dwordx4 v[222:223], off
	v_lshl_add_u64 v[222:223], s[14:15], 0, v[174:175]
	s_mov_b32 m0, s16
	s_nop 0
	global_load_lds_dwordx4 v[222:223], off
	v_lshl_add_u64 v[222:223], s[14:15], 0, v[144:145]
	s_add_i32 m0, s16, 0x2000
	s_nop 0
	global_load_lds_dwordx4 v[222:223], off
	v_lshl_add_u64 v[222:223], v[226:227], 0, s[10:11]
	s_mov_b32 m0, s35
	s_nop 0
	global_load_lds_dwordx4 v[222:223], off
	v_lshl_add_u64 v[222:223], v[228:229], 0, s[10:11]
	s_mov_b32 m0, s38
	s_nop 0
	global_load_lds_dwordx4 v[222:223], off
	s_waitcnt vmcnt(8)
	s_barrier
	s_waitcnt lgkmcnt(0)
	v_mfma_f32_16x16x32_bf16 v[96:99], v[100:103], v[190:193], v[96:99]
	v_mfma_f32_16x16x32_bf16 v[92:95], v[140:143], v[190:193], v[92:95]
	v_mfma_f32_16x16x32_bf16 v[88:91], v[100:103], v[198:201], v[88:91]
	v_mfma_f32_16x16x32_bf16 v[84:87], v[140:143], v[198:201], v[84:87]
	v_mfma_f32_16x16x32_bf16 v[80:83], v[100:103], v[206:209], v[80:83]
	v_mfma_f32_16x16x32_bf16 v[76:79], v[140:143], v[206:209], v[76:79]
	v_mfma_f32_16x16x32_bf16 v[72:75], v[100:103], v[214:217], v[72:75]
	v_mfma_f32_16x16x32_bf16 v[68:71], v[140:143], v[214:217], v[68:71]
	v_mfma_f32_16x16x32_bf16 v[96:99], v[104:107], v[194:197], v[96:99]
	v_mfma_f32_16x16x32_bf16 v[92:95], v[154:157], v[194:197], v[92:95]
	v_mfma_f32_16x16x32_bf16 v[88:91], v[104:107], v[202:205], v[88:91]
	v_mfma_f32_16x16x32_bf16 v[84:87], v[154:157], v[202:205], v[84:87]
	v_mfma_f32_16x16x32_bf16 v[80:83], v[104:107], v[210:213], v[80:83]
	v_mfma_f32_16x16x32_bf16 v[76:79], v[154:157], v[210:213], v[76:79]
	v_mfma_f32_16x16x32_bf16 v[72:75], v[104:107], v[218:221], v[72:75]
	v_mfma_f32_16x16x32_bf16 v[68:71], v[154:157], v[218:221], v[68:71]
	v_mfma_f32_16x16x32_bf16 v[32:35], v[158:161], v[190:193], v[32:35]
	v_mfma_f32_16x16x32_bf16 v[28:31], v[166:169], v[190:193], v[28:31]
	v_mfma_f32_16x16x32_bf16 v[24:27], v[158:161], v[198:201], v[24:27]
	v_mfma_f32_16x16x32_bf16 v[20:23], v[166:169], v[198:201], v[20:23]
	v_mfma_f32_16x16x32_bf16 v[16:19], v[158:161], v[206:209], v[16:19]
	v_mfma_f32_16x16x32_bf16 v[12:15], v[166:169], v[206:209], v[12:15]
	v_mfma_f32_16x16x32_bf16 v[8:11], v[158:161], v[214:217], v[8:11]
	v_mfma_f32_16x16x32_bf16 v[4:7], v[166:169], v[214:217], v[4:7]
	v_mfma_f32_16x16x32_bf16 v[32:35], v[162:165], v[194:197], v[32:35]
	v_mfma_f32_16x16x32_bf16 v[28:31], v[186:189], v[194:197], v[28:31]
	v_mfma_f32_16x16x32_bf16 v[24:27], v[162:165], v[202:205], v[24:27]
	v_mfma_f32_16x16x32_bf16 v[20:23], v[186:189], v[202:205], v[20:23]
	v_mfma_f32_16x16x32_bf16 v[16:19], v[162:165], v[210:213], v[16:19]
	v_mfma_f32_16x16x32_bf16 v[12:15], v[186:189], v[210:213], v[12:15]
	v_mfma_f32_16x16x32_bf16 v[8:11], v[162:165], v[218:221], v[8:11]
	v_mfma_f32_16x16x32_bf16 v[4:7], v[186:189], v[218:221], v[4:7]
	s_barrier
	s_add_i32 s58, s58, 2
	s_add_u32 s51, s51, 0x100
	s_addc_u32 s57, s57, 0
	s_add_u32 s0, s0, 0x100
	s_addc_u32 s1, s1, 0
	s_cmp_gt_u32 s58, 29
	s_cbranch_scc0 .LBB0_407
	s_and_b64 vcc, exec, s[46:47]
	s_cbranch_vccz .LBB0_410
	s_barrier

; #define PG8_STAGE(bufoff, gbase, voff) do { _Pragma("unroll") for (int _i = 0; _i < 2; ++_i) \
;         __builtin_amdgcn_global_load_lds((const unsigned*)((const char*)(gbase) + (voff)[_i]), (PG8_LAS unsigned*)(lds + (bufoff) + ldsw + _i * 8192), 16, 0, 0); } while (0)
; #define PG8_LDA(dst, b, h) do { _Pragma("unroll") for (int m = 0; m < 4; ++m) _Pragma("unroll") for (int k = 0; k < 2; ++k) dst[m][k] = *(const PG8_LAS bf16x8*)(lds + PG8_SA(b, h) + aoff + m * 2048 + k * 1024); } while (0)
; #define PG8_LDB(dst, b, h) do { _Pragma("unroll") for (int n = 0; n < 2; ++n) _Pragma("unroll") for (int k = 0; k < 2; ++k) dst[n][k] = *(const PG8_LAS bf16x8*)(lds + PG8_SB(b, h) + boff + n * 2048 + k * 1024); } while (0)
; #define PG8_MMA(ai, bj, At, Bt) do { __builtin_amdgcn_s_setprio(1); _Pragma("unroll") for (int m = 0; m < 4; ++m) _Pragma("unroll") for (int n = 0; n < 2; ++n) _Pragma("unroll") for (int k = 0; k < 2; ++k) \
;         acc[ai][bj][m][n] = __builtin_amdgcn_mfma_f32_16x16x32_bf16(Bt[n][k], At[m][k], acc[ai][bj][m][n], 0, 0, 0); __builtin_amdgcn_s_setprio(0); } while (0)
; #define PG8_WAIT_V(n) asm volatile("s_waitcnt vmcnt(" #n ")" ::: "memory")
; #define PG8_WAIT_L(n) asm volatile("s_waitcnt lgkmcnt(" #n ")" ::: "memory")
; #define PG8_BAR __builtin_amdgcn_s_barrier()
; #define PG8_SCHED __builtin_amdgcn_sched_barrier(0)
; template <class Epi, class Sched, bool ALIGN_EPI = false, bool SP2 = false>
; __device__ __forceinline__ void gemm_phase(PG8_LAS unsigned char* lds, const Gemm g, const Sched& S, const Epi& E) {
;     ...
;             PG8_LDB(B0, 0, 0); PG8_LDB(B1, 0, 1); PG8_SCHED; PG8_LDA(At, 0, 0); PG8_STAGE(PG8_SA(1, 1), a1 + hstep, voffA);
;             PG8_WAIT_V(8); PG8_WAIT_L(0); PG8_BAR; PG8_MMA(0, 0, At, B0); PG8_MMA(0, 1, At, B1); PG8_BAR; PG8_SCHED;
;             PG8_LDA(At, 0, 1); PG8_STAGE(PG8_SB(0, 0), b2, voffB); PG8_STAGE(PG8_SB(0, 1), b2 + hstep, voffB); PG8_STAGE(PG8_SA(0, 0), a2, voffA);
;             PG8_WAIT_V(8); PG8_WAIT_L(0); PG8_BAR; PG8_MMA(1, 0, At, B0); PG8_MMA(1, 1, At, B1); PG8_BAR; PG8_SCHED;
.Lprio_done_485:
.LBB0_485:
	s_add_u32 s14, s0, 0xfff00080
	s_addc_u32 s15, s1, -1
	s_add_i32 s61, 0, 0x10000
	s_cmp_eq_u32 s60, 60
	s_cselect_b32 s17, s23, s15
	s_cselect_b32 s16, s24, s14
	s_cselect_b32 s15, s25, s59
	s_cselect_b32 s14, s51, s53
	s_add_i32 s64, 0, 0x14000
	v_add_u32_e32 v144, s61, v188
	v_add_u32_e32 v170, s64, v188
	ds_read_b128 v[100:103], v144
	ds_read_b128 v[104:107], v144 offset:1024
	ds_read_b128 v[140:143], v144 offset:2048
	ds_read_b128 v[144:147], v144 offset:3072
	ds_read_b128 v[158:161], v170
	ds_read_b128 v[162:165], v170 offset:1024
	ds_read_b128 v[166:169], v170 offset:2048
	ds_read_b128 v[184:187], v170 offset:3072
	v_lshl_add_u64 v[170:171], s[0:1], 0, v[156:157]
	s_add_i32 m0, s29, 0xc000
	ds_read_b128 v[192:195], v190
	ds_read_b128 v[196:199], v190 offset:1024
	ds_read_b128 v[200:203], v190 offset:2048
	ds_read_b128 v[204:207], v190 offset:3072
	ds_read_b128 v[208:211], v190 offset:4096
	ds_read_b128 v[212:215], v190 offset:5120
	ds_read_b128 v[216:219], v190 offset:6144
	ds_read_b128 v[220:223], v190 offset:7168
	global_load_lds_dwordx4 v[170:171], off
	v_lshl_add_u64 v[170:171], s[0:1], 0, v[154:155]
	s_add_i32 m0, s29, 0xe000
	s_nop 0
	global_load_lds_dwordx4 v[170:171], off
	s_waitcnt vmcnt(8)
	s_barrier
	s_waitcnt lgkmcnt(0)
	v_mfma_f32_16x16x32_bf16 v[136:139], v[100:103], v[192:195], v[136:139]
	v_mfma_f32_16x16x32_bf16 v[132:135], v[140:143], v[192:195], v[132:135]
	v_mfma_f32_16x16x32_bf16 v[128:131], v[100:103], v[200:203], v[128:131]
	v_mfma_f32_16x16x32_bf16 v[124:127], v[140:143], v[200:203], v[124:127]
	v_mfma_f32_16x16x32_bf16 v[120:123], v[100:103], v[208:211], v[120:123]
	v_mfma_f32_16x16x32_bf16 v[116:119], v[140:143], v[208:211], v[116:119]
	v_mfma_f32_16x16x32_bf16 v[112:115], v[100:103], v[216:219], v[112:115]
	v_mfma_f32_16x16x32_bf16 v[108:111], v[140:143], v[216:219], v[108:111]
	v_mfma_f32_16x16x32_bf16 v[136:139], v[104:107], v[196:199], v[136:139]
	v_mfma_f32_16x16x32_bf16 v[132:135], v[144:147], v[196:199], v[132:135]
	v_mfma_f32_16x16x32_bf16 v[128:131], v[104:107], v[204:207], v[128:131]
	v_mfma_f32_16x16x32_bf16 v[124:127], v[144:147], v[204:207], v[124:127]
	v_mfma_f32_16x16x32_bf16 v[120:123], v[104:107], v[212:215], v[120:123]
	v_mfma_f32_16x16x32_bf16 v[116:119], v[144:147], v[212:215], v[116:119]
	v_mfma_f32_16x16x32_bf16 v[112:115], v[104:107], v[220:223], v[112:115]
	v_mfma_f32_16x16x32_bf16 v[108:111], v[144:147], v[220:223], v[108:111]
	v_mfma_f32_16x16x32_bf16 v[64:67], v[158:161], v[192:195], v[64:67]
	v_mfma_f32_16x16x32_bf16 v[60:63], v[166:169], v[192:195], v[60:63]
	v_mfma_f32_16x16x32_bf16 v[56:59], v[158:161], v[200:203], v[56:59]
	v_mfma_f32_16x16x32_bf16 v[52:55], v[166:169], v[200:203], v[52:55]
	v_mfma_f32_16x16x32_bf16 v[48:51], v[158:161], v[208:211], v[48:51]
	v_mfma_f32_16x16x32_bf16 v[44:47], v[166:169], v[208:211], v[44:47]
	v_mfma_f32_16x16x32_bf16 v[40:43], v[158:161], v[216:219], v[40:43]
	v_mfma_f32_16x16x32_bf16 v[36:39], v[166:169], v[216:219], v[36:39]
	v_mfma_f32_16x16x32_bf16 v[64:67], v[162:165], v[196:199], v[64:67]
	v_mfma_f32_16x16x32_bf16 v[60:63], v[184:187], v[196:199], v[60:63]
	v_mfma_f32_16x16x32_bf16 v[56:59], v[162:165], v[204:207], v[56:59]
	v_mfma_f32_16x16x32_bf16 v[52:55], v[184:187], v[204:207], v[52:55]
	v_mfma_f32_16x16x32_bf16 v[48:51], v[162:165], v[212:215], v[48:51]
	v_mfma_f32_16x16x32_bf16 v[44:47], v[184:187], v[212:215], v[44:47]
	v_mfma_f32_16x16x32_bf16 v[40:43], v[162:165], v[220:223], v[40:43]
	v_mfma_f32_16x16x32_bf16 v[36:39], v[184:187], v[220:223], v[36:39]
	s_barrier
	s_add_i32 s61, s61, s28
	v_lshl_add_u64 v[170:171], s[14:15], 0, v[174:175]
	s_mov_b32 m0, s61
	ds_read_b128 v[192:195], v190 offset:16384
	ds_read_b128 v[196:199], v190 offset:17408
	ds_read_b128 v[200:203], v190 offset:18432
	ds_read_b128 v[204:207], v190 offset:19456
	ds_read_b128 v[208:211], v190 offset:20480
	ds_read_b128 v[212:215], v190 offset:21504
	ds_read_b128 v[216:219], v190 offset:22528
	ds_read_b128 v[220:223], v190 offset:23552
	global_load_lds_dwordx4 v[170:171], off
	s_add_i32 m0, s61, 0x2000
	s_add_u32 s62, s14, 0x100000
	v_lshl_add_u64 v[224:225], s[14:15], 0, v[148:149]
	s_addc_u32 s63, s15, 0
	s_add_i32 s61, s64, s28
	global_load_lds_dwordx4 v[224:225], off
	v_lshl_add_u64 v[226:227], s[62:63], 0, v[174:175]
	s_mov_b32 m0, s61
	v_lshl_add_u64 v[228:229], s[16:17], 0, v[150:151]
	global_load_lds_dwordx4 v[226:227], off
	v_lshl_add_u64 v[226:227], s[62:63], 0, v[148:149]
	s_add_i32 m0, s61, 0x2000
	s_nop 0
	global_load_lds_dwordx4 v[226:227], off
	v_lshl_add_u64 v[226:227], s[16:17], 0, v[152:153]
	s_mov_b32 m0, s29
	s_nop 0
	global_load_lds_dwordx4 v[226:227], off
	s_mov_b32 m0, s30
	s_nop 0
	global_load_lds_dwordx4 v[228:229], off
	s_waitcnt vmcnt(8)
	s_barrier
; #define PG8_STAGE(bufoff, gbase, voff) do { _Pragma("unroll") for (int _i = 0; _i < 2; ++_i) \
;         __builtin_amdgcn_global_load_lds((const unsigned*)((const char*)(gbase) + (voff)[_i]), (PG8_LAS unsigned*)(lds + (bufoff) + ldsw + _i * 8192), 16, 0, 0); } while (0)
; #define PG8_LDA(dst, b, h) do { _Pragma("unroll") for (int m = 0; m < 4; ++m) _Pragma("unroll") for (int k = 0; k < 2; ++k) dst[m][k] = *(const PG8_LAS bf16x8*)(lds + PG8_SA(b, h) + aoff + m * 2048 + k * 1024); } while (0)
; #define PG8_LDB(dst, b, h) do { _Pragma("unroll") for (int n = 0; n < 2; ++n) _Pragma("unroll") for (int k = 0; k < 2; ++k) dst[n][k] = *(const PG8_LAS bf16x8*)(lds + PG8_SB(b, h) + boff + n * 2048 + k * 1024); } while (0)
; #define PG8_MMA(ai, bj, At, Bt) do { __builtin_amdgcn_s_setprio(1); _Pragma("unroll") for (int m = 0; m < 4; ++m) _Pragma("unroll") for (int n = 0; n < 2; ++n) _Pragma("unroll") for (int k = 0; k < 2; ++k) \
;         acc[ai][bj][m][n] = __builtin_amdgcn_mfma_f32_16x16x32_bf16(Bt[n][k], At[m][k], acc[ai][bj][m][n], 0, 0, 0); __builtin_amdgcn_s_setprio(0); } while (0)
; #define PG8_WAIT_V(n) asm volatile("s_waitcnt vmcnt(" #n ")" ::: "memory")
; #define PG8_WAIT_L(n) asm volatile("s_waitcnt lgkmcnt(" #n ")" ::: "memory")
; #define PG8_BAR __builtin_amdgcn_s_barrier()
; #define PG8_SCHED __builtin_amdgcn_sched_barrier(0)
; template <class Epi, class Sched, bool ALIGN_EPI = false, bool SP2 = false>
; __device__ __forceinline__ void gemm_phase(PG8_LAS unsigned char* lds, const Gemm g, const Sched& S, const Epi& E) {
;     ...
;             PG8_WAIT_V(8); PG8_WAIT_L(0); PG8_BAR; PG8_MMA(1, 0, At, B0); PG8_MMA(1, 1, At, B1); PG8_BAR; PG8_SCHED;
;             PG8_LDB(B0, 1, 0); PG8_LDB(B1, 1, 1); PG8_SCHED; PG8_LDA(At, 1, 0); PG8_STAGE(PG8_SA(0, 1), a2 + hstep, voffA);
;             PG8_WAIT_V(8); PG8_WAIT_L(0); PG8_BAR; PG8_MMA(0, 0, At, B0); PG8_MMA(0, 1, At, B1); PG8_BAR; PG8_SCHED;
	s_waitcnt lgkmcnt(0)
	v_mfma_f32_16x16x32_bf16 v[96:99], v[100:103], v[192:195], v[96:99]
	v_mfma_f32_16x16x32_bf16 v[92:95], v[140:143], v[192:195], v[92:95]
	v_mfma_f32_16x16x32_bf16 v[88:91], v[100:103], v[200:203], v[88:91]
	v_mfma_f32_16x16x32_bf16 v[84:87], v[140:143], v[200:203], v[84:87]
	v_mfma_f32_16x16x32_bf16 v[80:83], v[100:103], v[208:211], v[80:83]
	v_mfma_f32_16x16x32_bf16 v[76:79], v[140:143], v[208:211], v[76:79]
	v_mfma_f32_16x16x32_bf16 v[72:75], v[100:103], v[216:219], v[72:75]
	v_mfma_f32_16x16x32_bf16 v[68:71], v[140:143], v[216:219], v[68:71]
	v_mfma_f32_16x16x32_bf16 v[96:99], v[104:107], v[196:199], v[96:99]
	v_mfma_f32_16x16x32_bf16 v[92:95], v[144:147], v[196:199], v[92:95]
	v_mfma_f32_16x16x32_bf16 v[88:91], v[104:107], v[204:207], v[88:91]
	v_mfma_f32_16x16x32_bf16 v[84:87], v[144:147], v[204:207], v[84:87]
	v_mfma_f32_16x16x32_bf16 v[80:83], v[104:107], v[212:215], v[80:83]
	v_mfma_f32_16x16x32_bf16 v[76:79], v[144:147], v[212:215], v[76:79]
	v_mfma_f32_16x16x32_bf16 v[72:75], v[104:107], v[220:223], v[72:75]
	v_mfma_f32_16x16x32_bf16 v[68:71], v[144:147], v[220:223], v[68:71]
	v_mfma_f32_16x16x32_bf16 v[32:35], v[158:161], v[192:195], v[32:35]
	v_mfma_f32_16x16x32_bf16 v[28:31], v[166:169], v[192:195], v[28:31]
	v_mfma_f32_16x16x32_bf16 v[24:27], v[158:161], v[200:203], v[24:27]
	v_mfma_f32_16x16x32_bf16 v[20:23], v[166:169], v[200:203], v[20:23]
	v_mfma_f32_16x16x32_bf16 v[16:19], v[158:161], v[208:211], v[16:19]
	v_mfma_f32_16x16x32_bf16 v[12:15], v[166:169], v[208:211], v[12:15]
	v_mfma_f32_16x16x32_bf16 v[8:11], v[158:161], v[216:219], v[8:11]
	v_mfma_f32_16x16x32_bf16 v[4:7], v[166:169], v[216:219], v[4:7]
	v_mfma_f32_16x16x32_bf16 v[32:35], v[162:165], v[196:199], v[32:35]
	v_mfma_f32_16x16x32_bf16 v[28:31], v[184:187], v[196:199], v[28:31]
	v_mfma_f32_16x16x32_bf16 v[24:27], v[162:165], v[204:207], v[24:27]
	v_mfma_f32_16x16x32_bf16 v[20:23], v[184:187], v[204:207], v[20:23]
	v_mfma_f32_16x16x32_bf16 v[16:19], v[162:165], v[212:215], v[16:19]
	v_mfma_f32_16x16x32_bf16 v[12:15], v[184:187], v[212:215], v[12:15]
	v_mfma_f32_16x16x32_bf16 v[8:11], v[162:165], v[220:223], v[8:11]
	v_mfma_f32_16x16x32_bf16 v[4:7], v[184:187], v[220:223], v[4:7]
	s_barrier
	s_add_i32 s61, 0, 0x18000
	s_add_i32 s62, 0, 0x1c000
	v_add_u32_e32 v144, s61, v188
	v_add_u32_e32 v184, s62, v188
	ds_read_b128 v[100:103], v144
	ds_read_b128 v[104:107], v144 offset:1024
	ds_read_b128 v[140:143], v144 offset:2048
	ds_read_b128 v[144:147], v144 offset:3072
	ds_read_b128 v[158:161], v184
	ds_read_b128 v[162:165], v184 offset:1024
	ds_read_b128 v[166:169], v184 offset:2048
	ds_read_b128 v[184:187], v184 offset:3072
	s_add_u32 s16, s16, 0x100000
	s_addc_u32 s17, s17, 0
	s_mov_b32 m0, s31
	v_lshl_add_u64 v[230:231], s[16:17], 0, v[152:153]
	ds_read_b128 v[192:195], v190 offset:32768
	ds_read_b128 v[196:199], v190 offset:33792
	ds_read_b128 v[200:203], v190 offset:34816
	ds_read_b128 v[204:207], v190 offset:35840
	ds_read_b128 v[208:211], v190 offset:36864
	ds_read_b128 v[212:215], v190 offset:37888
	ds_read_b128 v[216:219], v190 offset:38912
	ds_read_b128 v[220:223], v190 offset:39936
	global_load_lds_dwordx4 v[230:231], off
	v_lshl_add_u64 v[230:231], s[16:17], 0, v[150:151]
	s_mov_b32 m0, s34
	s_nop 0
	global_load_lds_dwordx4 v[230:231], off
	s_waitcnt vmcnt(8)
	s_barrier
	s_waitcnt lgkmcnt(0)
	v_mfma_f32_16x16x32_bf16 v[136:139], v[100:103], v[192:195], v[136:139]
	v_mfma_f32_16x16x32_bf16 v[132:135], v[140:143], v[192:195], v[132:135]
	v_mfma_f32_16x16x32_bf16 v[128:131], v[100:103], v[200:203], v[128:131]
	v_mfma_f32_16x16x32_bf16 v[124:127], v[140:143], v[200:203], v[124:127]
	v_mfma_f32_16x16x32_bf16 v[120:123], v[100:103], v[208:211], v[120:123]
	v_mfma_f32_16x16x32_bf16 v[116:119], v[140:143], v[208:211], v[116:119]
	v_mfma_f32_16x16x32_bf16 v[112:115], v[100:103], v[216:219], v[112:115]
	v_mfma_f32_16x16x32_bf16 v[108:111], v[140:143], v[216:219], v[108:111]
	v_mfma_f32_16x16x32_bf16 v[136:139], v[104:107], v[196:199], v[136:139]
	v_mfma_f32_16x16x32_bf16 v[132:135], v[144:147], v[196:199], v[132:135]
	v_mfma_f32_16x16x32_bf16 v[128:131], v[104:107], v[204:207], v[128:131]
	v_mfma_f32_16x16x32_bf16 v[124:127], v[144:147], v[204:207], v[124:127]
	v_mfma_f32_16x16x32_bf16 v[120:123], v[104:107], v[212:215], v[120:123]
	v_mfma_f32_16x16x32_bf16 v[116:119], v[144:147], v[212:215], v[116:119]
	v_mfma_f32_16x16x32_bf16 v[112:115], v[104:107], v[220:223], v[112:115]
	v_mfma_f32_16x16x32_bf16 v[108:111], v[144:147], v[220:223], v[108:111]
	v_mfma_f32_16x16x32_bf16 v[64:67], v[158:161], v[192:195], v[64:67]
	v_mfma_f32_16x16x32_bf16 v[60:63], v[166:169], v[192:195], v[60:63]
	v_mfma_f32_16x16x32_bf16 v[56:59], v[158:161], v[200:203], v[56:59]
	v_mfma_f32_16x16x32_bf16 v[52:55], v[166:169], v[200:203], v[52:55]
	v_mfma_f32_16x16x32_bf16 v[48:51], v[158:161], v[208:211], v[48:51]
	v_mfma_f32_16x16x32_bf16 v[44:47], v[166:169], v[208:211], v[44:47]
	v_mfma_f32_16x16x32_bf16 v[40:43], v[158:161], v[216:219], v[40:43]
	v_mfma_f32_16x16x32_bf16 v[36:39], v[166:169], v[216:219], v[36:39]
	v_mfma_f32_16x16x32_bf16 v[64:67], v[162:165], v[196:199], v[64:67]
	v_mfma_f32_16x16x32_bf16 v[60:63], v[184:187], v[196:199], v[60:63]
	v_mfma_f32_16x16x32_bf16 v[56:59], v[162:165], v[204:207], v[56:59]
	v_mfma_f32_16x16x32_bf16 v[52:55], v[184:187], v[204:207], v[52:55]
	v_mfma_f32_16x16x32_bf16 v[48:51], v[162:165], v[212:215], v[48:51]
	v_mfma_f32_16x16x32_bf16 v[44:47], v[184:187], v[212:215], v[44:47]
	v_mfma_f32_16x16x32_bf16 v[40:43], v[162:165], v[220:223], v[40:43]
	v_mfma_f32_16x16x32_bf16 v[36:39], v[184:187], v[220:223], v[36:39]
	s_barrier
; #define PG8_STAGE(bufoff, gbase, voff) do { _Pragma("unroll") for (int _i = 0; _i < 2; ++_i) \
;         __builtin_amdgcn_global_load_lds((const unsigned*)((const char*)(gbase) + (voff)[_i]), (PG8_LAS unsigned*)(lds + (bufoff) + ldsw + _i * 8192), 16, 0, 0); } while (0)
; #define PG8_LDA(dst, b, h) do { _Pragma("unroll") for (int m = 0; m < 4; ++m) _Pragma("unroll") for (int k = 0; k < 2; ++k) dst[m][k] = *(const PG8_LAS bf16x8*)(lds + PG8_SA(b, h) + aoff + m * 2048 + k * 1024); } while (0)
; #define PG8_MMA(ai, bj, At, Bt) do { __builtin_amdgcn_s_setprio(1); _Pragma("unroll") for (int m = 0; m < 4; ++m) _Pragma("unroll") for (int n = 0; n < 2; ++n) _Pragma("unroll") for (int k = 0; k < 2; ++k) \
;         acc[ai][bj][m][n] = __builtin_amdgcn_mfma_f32_16x16x32_bf16(Bt[n][k], At[m][k], acc[ai][bj][m][n], 0, 0, 0); __builtin_amdgcn_s_setprio(0); } while (0)
; #define PG8_WAIT_V(n) asm volatile("s_waitcnt vmcnt(" #n ")" ::: "memory")
; #define PG8_WAIT_L(n) asm volatile("s_waitcnt lgkmcnt(" #n ")" ::: "memory")
; #define PG8_BAR __builtin_amdgcn_s_barrier()
; #define PG8_SCHED __builtin_amdgcn_sched_barrier(0)
; template <class Epi, class Sched, bool ALIGN_EPI = false, bool SP2 = false>
; __device__ __forceinline__ void gemm_phase(PG8_LAS unsigned char* lds, const Gemm g, const Sched& S, const Epi& E) {
;     ...
;         for (int t = 0; t < nt; t += 2) {
;             const bool last = (t == nt - 2);
;     ...
;             PG8_LDA(At, 1, 1); PG8_STAGE(PG8_SB(1, 0), b3, voffB); PG8_STAGE(PG8_SB(1, 1), b3 + hstep, voffB); PG8_STAGE(PG8_SA(1, 0), a3, voffA);
;             PG8_WAIT_V(8); PG8_WAIT_L(0); PG8_BAR; PG8_MMA(1, 0, At, B0); PG8_MMA(1, 1, At, B1); PG8_BAR; PG8_SCHED;
	s_add_i32 s16, s61, s28
	v_lshl_add_u64 v[170:171], v[170:171], 0, s[10:11]
	s_mov_b32 m0, s16
	ds_read_b128 v[192:195], v190 offset:49152
	ds_read_b128 v[196:199], v190 offset:50176
	ds_read_b128 v[200:203], v190 offset:51200
	ds_read_b128 v[204:207], v190 offset:52224
	ds_read_b128 v[208:211], v190 offset:53248
	ds_read_b128 v[212:215], v190 offset:54272
	ds_read_b128 v[216:219], v190 offset:55296
	ds_read_b128 v[220:223], v190 offset:56320
	global_load_lds_dwordx4 v[170:171], off
	s_add_i32 m0, s16, 0x2000
	s_add_u32 s14, s14, 0x100080
	v_lshl_add_u64 v[170:171], v[224:225], 0, s[10:11]
	s_addc_u32 s15, s15, 0
	s_add_i32 s16, s62, s28
	global_load_lds_dwordx4 v[170:171], off
	v_lshl_add_u64 v[170:171], s[14:15], 0, v[174:175]
	s_mov_b32 m0, s16
	s_nop 0
	global_load_lds_dwordx4 v[170:171], off
	v_lshl_add_u64 v[170:171], s[14:15], 0, v[148:149]
	s_add_i32 m0, s16, 0x2000
	s_nop 0
	global_load_lds_dwordx4 v[170:171], off
	v_lshl_add_u64 v[170:171], v[226:227], 0, s[10:11]
	s_mov_b32 m0, s35
	s_nop 0
	global_load_lds_dwordx4 v[170:171], off
	v_lshl_add_u64 v[170:171], v[228:229], 0, s[10:11]
	s_mov_b32 m0, s38
	s_nop 0
	global_load_lds_dwordx4 v[170:171], off
	s_waitcnt vmcnt(8)
	s_barrier
	s_waitcnt lgkmcnt(0)
	v_mfma_f32_16x16x32_bf16 v[96:99], v[100:103], v[192:195], v[96:99]
	v_mfma_f32_16x16x32_bf16 v[92:95], v[140:143], v[192:195], v[92:95]
	v_mfma_f32_16x16x32_bf16 v[88:91], v[100:103], v[200:203], v[88:91]
	v_mfma_f32_16x16x32_bf16 v[84:87], v[140:143], v[200:203], v[84:87]
	v_mfma_f32_16x16x32_bf16 v[80:83], v[100:103], v[208:211], v[80:83]
	v_mfma_f32_16x16x32_bf16 v[76:79], v[140:143], v[208:211], v[76:79]
	v_mfma_f32_16x16x32_bf16 v[72:75], v[100:103], v[216:219], v[72:75]
	v_mfma_f32_16x16x32_bf16 v[68:71], v[140:143], v[216:219], v[68:71]
	v_mfma_f32_16x16x32_bf16 v[96:99], v[104:107], v[196:199], v[96:99]
	v_mfma_f32_16x16x32_bf16 v[92:95], v[144:147], v[196:199], v[92:95]
	v_mfma_f32_16x16x32_bf16 v[88:91], v[104:107], v[204:207], v[88:91]
	v_mfma_f32_16x16x32_bf16 v[84:87], v[144:147], v[204:207], v[84:87]
	v_mfma_f32_16x16x32_bf16 v[80:83], v[104:107], v[212:215], v[80:83]
	v_mfma_f32_16x16x32_bf16 v[76:79], v[144:147], v[212:215], v[76:79]
	v_mfma_f32_16x16x32_bf16 v[72:75], v[104:107], v[220:223], v[72:75]
	v_mfma_f32_16x16x32_bf16 v[68:71], v[144:147], v[220:223], v[68:71]
	v_mfma_f32_16x16x32_bf16 v[32:35], v[158:161], v[192:195], v[32:35]
	v_mfma_f32_16x16x32_bf16 v[28:31], v[166:169], v[192:195], v[28:31]
	v_mfma_f32_16x16x32_bf16 v[24:27], v[158:161], v[200:203], v[24:27]
	v_mfma_f32_16x16x32_bf16 v[20:23], v[166:169], v[200:203], v[20:23]
	v_mfma_f32_16x16x32_bf16 v[16:19], v[158:161], v[208:211], v[16:19]
	v_mfma_f32_16x16x32_bf16 v[12:15], v[166:169], v[208:211], v[12:15]
	v_mfma_f32_16x16x32_bf16 v[8:11], v[158:161], v[216:219], v[8:11]
	v_mfma_f32_16x16x32_bf16 v[4:7], v[166:169], v[216:219], v[4:7]
	v_mfma_f32_16x16x32_bf16 v[32:35], v[162:165], v[196:199], v[32:35]
	v_mfma_f32_16x16x32_bf16 v[28:31], v[184:187], v[196:199], v[28:31]
	v_mfma_f32_16x16x32_bf16 v[24:27], v[162:165], v[204:207], v[24:27]
	v_mfma_f32_16x16x32_bf16 v[20:23], v[184:187], v[204:207], v[20:23]
	v_mfma_f32_16x16x32_bf16 v[16:19], v[162:165], v[212:215], v[16:19]
	v_mfma_f32_16x16x32_bf16 v[12:15], v[184:187], v[212:215], v[12:15]
	v_mfma_f32_16x16x32_bf16 v[8:11], v[162:165], v[220:223], v[8:11]
	v_mfma_f32_16x16x32_bf16 v[4:7], v[184:187], v[220:223], v[4:7]
	s_barrier
	s_add_i32 s60, s60, 2
	s_add_u32 s53, s53, 0x100
	s_addc_u32 s59, s59, 0
	s_add_u32 s0, s0, 0x100
	s_addc_u32 s1, s1, 0
	s_cmp_gt_u32 s60, 61
	s_cbranch_scc0 .LBB0_485
	s_and_b64 vcc, exec, s[48:49]
	s_cbranch_vccz .LBB0_488
	s_barrier

; #define PG8_STAGE(bufoff, gbase, voff) do { _Pragma("unroll") for (int _i = 0; _i < 2; ++_i) \
;         __builtin_amdgcn_global_load_lds((const unsigned*)((const char*)(gbase) + (voff)[_i]), (PG8_LAS unsigned*)(lds + (bufoff) + ldsw + _i * 8192), 16, 0, 0); } while (0)
; #define PG8_LDA(dst, b, h) do { _Pragma("unroll") for (int m = 0; m < 4; ++m) _Pragma("unroll") for (int k = 0; k < 2; ++k) dst[m][k] = *(const PG8_LAS bf16x8*)(lds + PG8_SA(b, h) + aoff + m * 2048 + k * 1024); } while (0)
; #define PG8_LDB(dst, b, h) do { _Pragma("unroll") for (int n = 0; n < 2; ++n) _Pragma("unroll") for (int k = 0; k < 2; ++k) dst[n][k] = *(const PG8_LAS bf16x8*)(lds + PG8_SB(b, h) + boff + n * 2048 + k * 1024); } while (0)
; #define PG8_MMA(ai, bj, At, Bt) do { __builtin_amdgcn_s_setprio(1); _Pragma("unroll") for (int m = 0; m < 4; ++m) _Pragma("unroll") for (int n = 0; n < 2; ++n) _Pragma("unroll") for (int k = 0; k < 2; ++k) \
;         acc[ai][bj][m][n] = __builtin_amdgcn_mfma_f32_16x16x32_bf16(Bt[n][k], At[m][k], acc[ai][bj][m][n], 0, 0, 0); __builtin_amdgcn_s_setprio(0); } while (0)
; #define PG8_WAIT_V(n) asm volatile("s_waitcnt vmcnt(" #n ")" ::: "memory")
; #define PG8_WAIT_L(n) asm volatile("s_waitcnt lgkmcnt(" #n ")" ::: "memory")
; #define PG8_BAR __builtin_amdgcn_s_barrier()
; #define PG8_SCHED __builtin_amdgcn_sched_barrier(0)
; template <class Epi, class Sched, bool ALIGN_EPI = false, bool SP2 = false>
; __device__ __forceinline__ void gemm_phase(PG8_LAS unsigned char* lds, const Gemm g, const Sched& S, const Epi& E) {
;     ...
;             PG8_LDB(B0, 0, 0); PG8_LDB(B1, 0, 1); PG8_SCHED; PG8_LDA(At, 0, 0); PG8_STAGE(PG8_SA(1, 1), a1 + hstep, voffA);
;             PG8_WAIT_V(8); PG8_WAIT_L(0); PG8_BAR; PG8_MMA(0, 0, At, B0); PG8_MMA(0, 1, At, B1); PG8_BAR; PG8_SCHED;
;             PG8_LDA(At, 0, 1); PG8_STAGE(PG8_SB(0, 0), b2, voffB); PG8_STAGE(PG8_SB(0, 1), b2 + hstep, voffB); PG8_STAGE(PG8_SA(0, 0), a2, voffA);
;             PG8_WAIT_V(8); PG8_WAIT_L(0); PG8_BAR; PG8_MMA(1, 0, At, B0); PG8_MMA(1, 1, At, B1); PG8_BAR; PG8_SCHED;
.Lprio_done_563:
.LBB0_563:
	s_add_u32 s18, s0, 0xfff80080
	s_addc_u32 s19, s1, -1
	s_add_i32 s64, 0, 0x10000
	s_cmp_eq_u32 s63, 28
	s_cselect_b32 s27, s39, s19
	s_cselect_b32 s26, s59, s18
	s_cselect_b32 s19, s37, s62
	s_cselect_b32 s18, s60, s61
	s_add_i32 s66, 0, 0x14000
	v_add_u32_e32 v144, s64, v167
	v_add_u32_e32 v170, s66, v167
	ds_read_b128 v[132:135], v144
	ds_read_b128 v[136:139], v144 offset:1024
	ds_read_b128 v[140:143], v144 offset:2048
	ds_read_b128 v[144:147], v144 offset:3072
	ds_read_b128 v[158:161], v170
	ds_read_b128 v[162:165], v170 offset:1024
	ds_read_b128 v[184:187], v170 offset:2048
	ds_read_b128 v[188:191], v170 offset:3072
	v_lshl_add_u64 v[170:171], s[0:1], 0, v[156:157]
	s_add_i32 m0, s49, 0xc000
	ds_read_b128 v[192:195], v169
	ds_read_b128 v[196:199], v169 offset:1024
	ds_read_b128 v[200:203], v169 offset:2048
	ds_read_b128 v[204:207], v169 offset:3072
	ds_read_b128 v[208:211], v169 offset:4096
	ds_read_b128 v[212:215], v169 offset:5120
	ds_read_b128 v[216:219], v169 offset:6144
	ds_read_b128 v[220:223], v169 offset:7168
	global_load_lds_dwordx4 v[170:171], off
	v_lshl_add_u64 v[170:171], s[0:1], 0, v[154:155]
	s_add_i32 m0, s49, 0xe000
	s_nop 0
	global_load_lds_dwordx4 v[170:171], off
	s_waitcnt vmcnt(8)
	s_barrier
	s_waitcnt lgkmcnt(0)
	v_mfma_f32_16x16x32_bf16 v[128:131], v[132:135], v[192:195], v[128:131]
	v_mfma_f32_16x16x32_bf16 v[124:127], v[140:143], v[192:195], v[124:127]
	v_mfma_f32_16x16x32_bf16 v[112:115], v[132:135], v[200:203], v[112:115]
	v_mfma_f32_16x16x32_bf16 v[108:111], v[140:143], v[200:203], v[108:111]
	v_mfma_f32_16x16x32_bf16 v[96:99], v[132:135], v[208:211], v[96:99]
	v_mfma_f32_16x16x32_bf16 v[92:95], v[140:143], v[208:211], v[92:95]
	v_mfma_f32_16x16x32_bf16 v[80:83], v[132:135], v[216:219], v[80:83]
	v_mfma_f32_16x16x32_bf16 v[76:79], v[140:143], v[216:219], v[76:79]
	v_mfma_f32_16x16x32_bf16 v[128:131], v[136:139], v[196:199], v[128:131]
	v_mfma_f32_16x16x32_bf16 v[124:127], v[144:147], v[196:199], v[124:127]
	v_mfma_f32_16x16x32_bf16 v[112:115], v[136:139], v[204:207], v[112:115]
	v_mfma_f32_16x16x32_bf16 v[108:111], v[144:147], v[204:207], v[108:111]
	v_mfma_f32_16x16x32_bf16 v[96:99], v[136:139], v[212:215], v[96:99]
	v_mfma_f32_16x16x32_bf16 v[92:95], v[144:147], v[212:215], v[92:95]
	v_mfma_f32_16x16x32_bf16 v[80:83], v[136:139], v[220:223], v[80:83]
	v_mfma_f32_16x16x32_bf16 v[76:79], v[144:147], v[220:223], v[76:79]
	v_mfma_f32_16x16x32_bf16 v[120:123], v[158:161], v[192:195], v[120:123]
	v_mfma_f32_16x16x32_bf16 v[116:119], v[184:187], v[192:195], v[116:119]
	v_mfma_f32_16x16x32_bf16 v[104:107], v[158:161], v[200:203], v[104:107]
	v_mfma_f32_16x16x32_bf16 v[100:103], v[184:187], v[200:203], v[100:103]
	v_mfma_f32_16x16x32_bf16 v[88:91], v[158:161], v[208:211], v[88:91]
	v_mfma_f32_16x16x32_bf16 v[84:87], v[184:187], v[208:211], v[84:87]
	v_mfma_f32_16x16x32_bf16 v[72:75], v[158:161], v[216:219], v[72:75]
	v_mfma_f32_16x16x32_bf16 v[68:71], v[184:187], v[216:219], v[68:71]
	v_mfma_f32_16x16x32_bf16 v[120:123], v[162:165], v[196:199], v[120:123]
	v_mfma_f32_16x16x32_bf16 v[116:119], v[188:191], v[196:199], v[116:119]
	v_mfma_f32_16x16x32_bf16 v[104:107], v[162:165], v[204:207], v[104:107]
	v_mfma_f32_16x16x32_bf16 v[100:103], v[188:191], v[204:207], v[100:103]
	v_mfma_f32_16x16x32_bf16 v[88:91], v[162:165], v[212:215], v[88:91]
	v_mfma_f32_16x16x32_bf16 v[84:87], v[188:191], v[212:215], v[84:87]
	v_mfma_f32_16x16x32_bf16 v[72:75], v[162:165], v[220:223], v[72:75]
	v_mfma_f32_16x16x32_bf16 v[68:71], v[188:191], v[220:223], v[68:71]
	s_barrier
	s_add_i32 s64, s64, s48
	v_lshl_add_u64 v[170:171], s[18:19], 0, v[174:175]
	s_mov_b32 m0, s64
	ds_read_b128 v[192:195], v169 offset:16384
	ds_read_b128 v[196:199], v169 offset:17408
	ds_read_b128 v[200:203], v169 offset:18432
	ds_read_b128 v[204:207], v169 offset:19456
	ds_read_b128 v[208:211], v169 offset:20480
	ds_read_b128 v[212:215], v169 offset:21504
	ds_read_b128 v[216:219], v169 offset:22528
	ds_read_b128 v[220:223], v169 offset:23552
	global_load_lds_dwordx4 v[170:171], off
	s_add_i32 m0, s64, 0x2000
	s_add_u32 s64, s18, 0x80000
	v_lshl_add_u64 v[224:225], s[18:19], 0, v[148:149]
	s_addc_u32 s65, s19, 0
	s_add_i32 s66, s66, s48
	global_load_lds_dwordx4 v[224:225], off
	v_lshl_add_u64 v[226:227], s[64:65], 0, v[174:175]
	s_mov_b32 m0, s66
	v_lshl_add_u64 v[228:229], s[26:27], 0, v[150:151]
	global_load_lds_dwordx4 v[226:227], off
	v_lshl_add_u64 v[226:227], s[64:65], 0, v[148:149]
	s_add_i32 m0, s66, 0x2000
	s_nop 0
	global_load_lds_dwordx4 v[226:227], off
	v_lshl_add_u64 v[226:227], s[26:27], 0, v[152:153]
	s_mov_b32 m0, s49
	s_nop 0
	global_load_lds_dwordx4 v[226:227], off
	s_mov_b32 m0, s50
	s_nop 0
	global_load_lds_dwordx4 v[228:229], off
	s_waitcnt vmcnt(8)
	s_barrier
; #define PG8_STAGE(bufoff, gbase, voff) do { _Pragma("unroll") for (int _i = 0; _i < 2; ++_i) \
;         __builtin_amdgcn_global_load_lds((const unsigned*)((const char*)(gbase) + (voff)[_i]), (PG8_LAS unsigned*)(lds + (bufoff) + ldsw + _i * 8192), 16, 0, 0); } while (0)
; #define PG8_LDA(dst, b, h) do { _Pragma("unroll") for (int m = 0; m < 4; ++m) _Pragma("unroll") for (int k = 0; k < 2; ++k) dst[m][k] = *(const PG8_LAS bf16x8*)(lds + PG8_SA(b, h) + aoff + m * 2048 + k * 1024); } while (0)
; #define PG8_LDB(dst, b, h) do { _Pragma("unroll") for (int n = 0; n < 2; ++n) _Pragma("unroll") for (int k = 0; k < 2; ++k) dst[n][k] = *(const PG8_LAS bf16x8*)(lds + PG8_SB(b, h) + boff + n * 2048 + k * 1024); } while (0)
; #define PG8_MMA(ai, bj, At, Bt) do { __builtin_amdgcn_s_setprio(1); _Pragma("unroll") for (int m = 0; m < 4; ++m) _Pragma("unroll") for (int n = 0; n < 2; ++n) _Pragma("unroll") for (int k = 0; k < 2; ++k) \
;         acc[ai][bj][m][n] = __builtin_amdgcn_mfma_f32_16x16x32_bf16(Bt[n][k], At[m][k], acc[ai][bj][m][n], 0, 0, 0); __builtin_amdgcn_s_setprio(0); } while (0)
; #define PG8_WAIT_V(n) asm volatile("s_waitcnt vmcnt(" #n ")" ::: "memory")
; #define PG8_WAIT_L(n) asm volatile("s_waitcnt lgkmcnt(" #n ")" ::: "memory")
; #define PG8_BAR __builtin_amdgcn_s_barrier()
; #define PG8_SCHED __builtin_amdgcn_sched_barrier(0)
; template <class Epi, class Sched, bool ALIGN_EPI = false, bool SP2 = false>
; __device__ __forceinline__ void gemm_phase(PG8_LAS unsigned char* lds, const Gemm g, const Sched& S, const Epi& E) {
;     ...
;             PG8_WAIT_V(8); PG8_WAIT_L(0); PG8_BAR; PG8_MMA(1, 0, At, B0); PG8_MMA(1, 1, At, B1); PG8_BAR; PG8_SCHED;
;             PG8_LDB(B0, 1, 0); PG8_LDB(B1, 1, 1); PG8_SCHED; PG8_LDA(At, 1, 0); PG8_STAGE(PG8_SA(0, 1), a2 + hstep, voffA);
;             PG8_WAIT_V(8); PG8_WAIT_L(0); PG8_BAR; PG8_MMA(0, 0, At, B0); PG8_MMA(0, 1, At, B1); PG8_BAR; PG8_SCHED;
	s_waitcnt lgkmcnt(0)
	v_mfma_f32_16x16x32_bf16 v[64:67], v[132:135], v[192:195], v[64:67]
	v_mfma_f32_16x16x32_bf16 v[60:63], v[140:143], v[192:195], v[60:63]
	v_mfma_f32_16x16x32_bf16 v[48:51], v[132:135], v[200:203], v[48:51]
	v_mfma_f32_16x16x32_bf16 v[44:47], v[140:143], v[200:203], v[44:47]
	v_mfma_f32_16x16x32_bf16 v[32:35], v[132:135], v[208:211], v[32:35]
	v_mfma_f32_16x16x32_bf16 v[28:31], v[140:143], v[208:211], v[28:31]
	v_mfma_f32_16x16x32_bf16 v[16:19], v[132:135], v[216:219], v[16:19]
	v_mfma_f32_16x16x32_bf16 v[12:15], v[140:143], v[216:219], v[12:15]
	v_mfma_f32_16x16x32_bf16 v[64:67], v[136:139], v[196:199], v[64:67]
	v_mfma_f32_16x16x32_bf16 v[60:63], v[144:147], v[196:199], v[60:63]
	v_mfma_f32_16x16x32_bf16 v[48:51], v[136:139], v[204:207], v[48:51]
	v_mfma_f32_16x16x32_bf16 v[44:47], v[144:147], v[204:207], v[44:47]
	v_mfma_f32_16x16x32_bf16 v[32:35], v[136:139], v[212:215], v[32:35]
	v_mfma_f32_16x16x32_bf16 v[28:31], v[144:147], v[212:215], v[28:31]
	v_mfma_f32_16x16x32_bf16 v[16:19], v[136:139], v[220:223], v[16:19]
	v_mfma_f32_16x16x32_bf16 v[12:15], v[144:147], v[220:223], v[12:15]
	v_mfma_f32_16x16x32_bf16 v[56:59], v[158:161], v[192:195], v[56:59]
	v_mfma_f32_16x16x32_bf16 v[52:55], v[184:187], v[192:195], v[52:55]
	v_mfma_f32_16x16x32_bf16 v[40:43], v[158:161], v[200:203], v[40:43]
	v_mfma_f32_16x16x32_bf16 v[36:39], v[184:187], v[200:203], v[36:39]
	v_mfma_f32_16x16x32_bf16 v[24:27], v[158:161], v[208:211], v[24:27]
	v_mfma_f32_16x16x32_bf16 v[20:23], v[184:187], v[208:211], v[20:23]
	v_mfma_f32_16x16x32_bf16 v[8:11], v[158:161], v[216:219], v[8:11]
	v_mfma_f32_16x16x32_bf16 v[4:7], v[184:187], v[216:219], v[4:7]
	v_mfma_f32_16x16x32_bf16 v[56:59], v[162:165], v[196:199], v[56:59]
	v_mfma_f32_16x16x32_bf16 v[52:55], v[188:191], v[196:199], v[52:55]
	v_mfma_f32_16x16x32_bf16 v[40:43], v[162:165], v[204:207], v[40:43]
	v_mfma_f32_16x16x32_bf16 v[36:39], v[188:191], v[204:207], v[36:39]
	v_mfma_f32_16x16x32_bf16 v[24:27], v[162:165], v[212:215], v[24:27]
	v_mfma_f32_16x16x32_bf16 v[20:23], v[188:191], v[212:215], v[20:23]
	v_mfma_f32_16x16x32_bf16 v[8:11], v[162:165], v[220:223], v[8:11]
	v_mfma_f32_16x16x32_bf16 v[4:7], v[188:191], v[220:223], v[4:7]
	s_barrier
	s_add_i32 s64, 0, 0x18000
	s_add_i32 s65, 0, 0x1c000
	v_add_u32_e32 v144, s64, v167
	v_add_u32_e32 v179, s65, v167
	ds_read_b128 v[132:135], v144
	ds_read_b128 v[136:139], v144 offset:1024
	ds_read_b128 v[140:143], v144 offset:2048
	ds_read_b128 v[144:147], v144 offset:3072
	ds_read_b128 v[158:161], v179
	ds_read_b128 v[162:165], v179 offset:1024
	ds_read_b128 v[184:187], v179 offset:2048
	ds_read_b128 v[188:191], v179 offset:3072
	s_add_u32 s26, s26, 0x80000
	s_addc_u32 s27, s27, 0
	s_mov_b32 m0, s51
	v_lshl_add_u64 v[230:231], s[26:27], 0, v[152:153]
	ds_read_b128 v[192:195], v169 offset:32768
	ds_read_b128 v[196:199], v169 offset:33792
	ds_read_b128 v[200:203], v169 offset:34816
	ds_read_b128 v[204:207], v169 offset:35840
	ds_read_b128 v[208:211], v169 offset:36864
	ds_read_b128 v[212:215], v169 offset:37888
	ds_read_b128 v[216:219], v169 offset:38912
	ds_read_b128 v[220:223], v169 offset:39936
	global_load_lds_dwordx4 v[230:231], off
	v_lshl_add_u64 v[230:231], s[26:27], 0, v[150:151]
	s_mov_b32 m0, s52
	s_nop 0
	global_load_lds_dwordx4 v[230:231], off
	s_waitcnt vmcnt(8)
	s_barrier
	s_waitcnt lgkmcnt(0)
	v_mfma_f32_16x16x32_bf16 v[128:131], v[132:135], v[192:195], v[128:131]
	v_mfma_f32_16x16x32_bf16 v[124:127], v[140:143], v[192:195], v[124:127]
	v_mfma_f32_16x16x32_bf16 v[112:115], v[132:135], v[200:203], v[112:115]
	v_mfma_f32_16x16x32_bf16 v[108:111], v[140:143], v[200:203], v[108:111]
	v_mfma_f32_16x16x32_bf16 v[96:99], v[132:135], v[208:211], v[96:99]
	v_mfma_f32_16x16x32_bf16 v[92:95], v[140:143], v[208:211], v[92:95]
	v_mfma_f32_16x16x32_bf16 v[80:83], v[132:135], v[216:219], v[80:83]
	v_mfma_f32_16x16x32_bf16 v[76:79], v[140:143], v[216:219], v[76:79]
	v_mfma_f32_16x16x32_bf16 v[128:131], v[136:139], v[196:199], v[128:131]
	v_mfma_f32_16x16x32_bf16 v[124:127], v[144:147], v[196:199], v[124:127]
	v_mfma_f32_16x16x32_bf16 v[112:115], v[136:139], v[204:207], v[112:115]
	v_mfma_f32_16x16x32_bf16 v[108:111], v[144:147], v[204:207], v[108:111]
	v_mfma_f32_16x16x32_bf16 v[96:99], v[136:139], v[212:215], v[96:99]
	v_mfma_f32_16x16x32_bf16 v[92:95], v[144:147], v[212:215], v[92:95]
	v_mfma_f32_16x16x32_bf16 v[80:83], v[136:139], v[220:223], v[80:83]
	v_mfma_f32_16x16x32_bf16 v[76:79], v[144:147], v[220:223], v[76:79]
	v_mfma_f32_16x16x32_bf16 v[120:123], v[158:161], v[192:195], v[120:123]
	v_mfma_f32_16x16x32_bf16 v[116:119], v[184:187], v[192:195], v[116:119]
	v_mfma_f32_16x16x32_bf16 v[104:107], v[158:161], v[200:203], v[104:107]
	v_mfma_f32_16x16x32_bf16 v[100:103], v[184:187], v[200:203], v[100:103]
	v_mfma_f32_16x16x32_bf16 v[88:91], v[158:161], v[208:211], v[88:91]
	v_mfma_f32_16x16x32_bf16 v[84:87], v[184:187], v[208:211], v[84:87]
	v_mfma_f32_16x16x32_bf16 v[72:75], v[158:161], v[216:219], v[72:75]
	v_mfma_f32_16x16x32_bf16 v[68:71], v[184:187], v[216:219], v[68:71]
	v_mfma_f32_16x16x32_bf16 v[120:123], v[162:165], v[196:199], v[120:123]
	v_mfma_f32_16x16x32_bf16 v[116:119], v[188:191], v[196:199], v[116:119]
	v_mfma_f32_16x16x32_bf16 v[104:107], v[162:165], v[204:207], v[104:107]
	v_mfma_f32_16x16x32_bf16 v[100:103], v[188:191], v[204:207], v[100:103]
	v_mfma_f32_16x16x32_bf16 v[88:91], v[162:165], v[212:215], v[88:91]
	v_mfma_f32_16x16x32_bf16 v[84:87], v[188:191], v[212:215], v[84:87]
	v_mfma_f32_16x16x32_bf16 v[72:75], v[162:165], v[220:223], v[72:75]
	v_mfma_f32_16x16x32_bf16 v[68:71], v[188:191], v[220:223], v[68:71]
	s_barrier
; #define PG8_STAGE(bufoff, gbase, voff) do { _Pragma("unroll") for (int _i = 0; _i < 2; ++_i) \
;         __builtin_amdgcn_global_load_lds((const unsigned*)((const char*)(gbase) + (voff)[_i]), (PG8_LAS unsigned*)(lds + (bufoff) + ldsw + _i * 8192), 16, 0, 0); } while (0)
; #define PG8_LDA(dst, b, h) do { _Pragma("unroll") for (int m = 0; m < 4; ++m) _Pragma("unroll") for (int k = 0; k < 2; ++k) dst[m][k] = *(const PG8_LAS bf16x8*)(lds + PG8_SA(b, h) + aoff + m * 2048 + k * 1024); } while (0)
; #define PG8_MMA(ai, bj, At, Bt) do { __builtin_amdgcn_s_setprio(1); _Pragma("unroll") for (int m = 0; m < 4; ++m) _Pragma("unroll") for (int n = 0; n < 2; ++n) _Pragma("unroll") for (int k = 0; k < 2; ++k) \
;         acc[ai][bj][m][n] = __builtin_amdgcn_mfma_f32_16x16x32_bf16(Bt[n][k], At[m][k], acc[ai][bj][m][n], 0, 0, 0); __builtin_amdgcn_s_setprio(0); } while (0)
; #define PG8_WAIT_V(n) asm volatile("s_waitcnt vmcnt(" #n ")" ::: "memory")
; #define PG8_WAIT_L(n) asm volatile("s_waitcnt lgkmcnt(" #n ")" ::: "memory")
; #define PG8_BAR __builtin_amdgcn_s_barrier()
; #define PG8_SCHED __builtin_amdgcn_sched_barrier(0)
; template <class Epi, class Sched, bool ALIGN_EPI = false, bool SP2 = false>
; __device__ __forceinline__ void gemm_phase(PG8_LAS unsigned char* lds, const Gemm g, const Sched& S, const Epi& E) {
;     ...
;         for (int t = 0; t < nt; t += 2) {
;             const bool last = (t == nt - 2);
;     ...
;             PG8_LDA(At, 1, 1); PG8_STAGE(PG8_SB(1, 0), b3, voffB); PG8_STAGE(PG8_SB(1, 1), b3 + hstep, voffB); PG8_STAGE(PG8_SA(1, 0), a3, voffA);
;             PG8_WAIT_V(8); PG8_WAIT_L(0); PG8_BAR; PG8_MMA(1, 0, At, B0); PG8_MMA(1, 1, At, B1); PG8_BAR; PG8_SCHED;
	s_add_i32 s26, s64, s48
	v_lshl_add_u64 v[170:171], v[170:171], 0, s[10:11]
	s_mov_b32 m0, s26
	ds_read_b128 v[192:195], v169 offset:49152
	ds_read_b128 v[196:199], v169 offset:50176
	ds_read_b128 v[200:203], v169 offset:51200
	ds_read_b128 v[204:207], v169 offset:52224
	ds_read_b128 v[208:211], v169 offset:53248
	ds_read_b128 v[212:215], v169 offset:54272
	ds_read_b128 v[216:219], v169 offset:55296
	ds_read_b128 v[220:223], v169 offset:56320
	global_load_lds_dwordx4 v[170:171], off
	s_add_i32 m0, s26, 0x2000
	s_add_u32 s18, s18, 0x80080
	v_lshl_add_u64 v[170:171], v[224:225], 0, s[10:11]
	s_addc_u32 s19, s19, 0
	s_add_i32 s26, s65, s48
	global_load_lds_dwordx4 v[170:171], off
	v_lshl_add_u64 v[170:171], s[18:19], 0, v[174:175]
	s_mov_b32 m0, s26
	s_nop 0
	global_load_lds_dwordx4 v[170:171], off
	v_lshl_add_u64 v[170:171], s[18:19], 0, v[148:149]
	s_add_i32 m0, s26, 0x2000
	s_nop 0
	global_load_lds_dwordx4 v[170:171], off
	v_lshl_add_u64 v[170:171], v[226:227], 0, s[10:11]
	s_mov_b32 m0, s54
	s_nop 0
	global_load_lds_dwordx4 v[170:171], off
	v_lshl_add_u64 v[170:171], v[228:229], 0, s[10:11]
	s_mov_b32 m0, s55
	s_nop 0
	global_load_lds_dwordx4 v[170:171], off
	s_waitcnt vmcnt(8)
	s_barrier
	s_waitcnt lgkmcnt(0)
	v_mfma_f32_16x16x32_bf16 v[64:67], v[132:135], v[192:195], v[64:67]
	v_mfma_f32_16x16x32_bf16 v[60:63], v[140:143], v[192:195], v[60:63]
	v_mfma_f32_16x16x32_bf16 v[48:51], v[132:135], v[200:203], v[48:51]
	v_mfma_f32_16x16x32_bf16 v[44:47], v[140:143], v[200:203], v[44:47]
	v_mfma_f32_16x16x32_bf16 v[32:35], v[132:135], v[208:211], v[32:35]
	v_mfma_f32_16x16x32_bf16 v[28:31], v[140:143], v[208:211], v[28:31]
	v_mfma_f32_16x16x32_bf16 v[16:19], v[132:135], v[216:219], v[16:19]
	v_mfma_f32_16x16x32_bf16 v[12:15], v[140:143], v[216:219], v[12:15]
	v_mfma_f32_16x16x32_bf16 v[64:67], v[136:139], v[196:199], v[64:67]
	v_mfma_f32_16x16x32_bf16 v[60:63], v[144:147], v[196:199], v[60:63]
	v_mfma_f32_16x16x32_bf16 v[48:51], v[136:139], v[204:207], v[48:51]
	v_mfma_f32_16x16x32_bf16 v[44:47], v[144:147], v[204:207], v[44:47]
	v_mfma_f32_16x16x32_bf16 v[32:35], v[136:139], v[212:215], v[32:35]
	v_mfma_f32_16x16x32_bf16 v[28:31], v[144:147], v[212:215], v[28:31]
	v_mfma_f32_16x16x32_bf16 v[16:19], v[136:139], v[220:223], v[16:19]
	v_mfma_f32_16x16x32_bf16 v[12:15], v[144:147], v[220:223], v[12:15]
	v_mfma_f32_16x16x32_bf16 v[56:59], v[158:161], v[192:195], v[56:59]
	v_mfma_f32_16x16x32_bf16 v[52:55], v[184:187], v[192:195], v[52:55]
	v_mfma_f32_16x16x32_bf16 v[40:43], v[158:161], v[200:203], v[40:43]
	v_mfma_f32_16x16x32_bf16 v[36:39], v[184:187], v[200:203], v[36:39]
	v_mfma_f32_16x16x32_bf16 v[24:27], v[158:161], v[208:211], v[24:27]
	v_mfma_f32_16x16x32_bf16 v[20:23], v[184:187], v[208:211], v[20:23]
	v_mfma_f32_16x16x32_bf16 v[8:11], v[158:161], v[216:219], v[8:11]
	v_mfma_f32_16x16x32_bf16 v[4:7], v[184:187], v[216:219], v[4:7]
	v_mfma_f32_16x16x32_bf16 v[56:59], v[162:165], v[196:199], v[56:59]
	v_mfma_f32_16x16x32_bf16 v[52:55], v[188:191], v[196:199], v[52:55]
	v_mfma_f32_16x16x32_bf16 v[40:43], v[162:165], v[204:207], v[40:43]
	v_mfma_f32_16x16x32_bf16 v[36:39], v[188:191], v[204:207], v[36:39]
	v_mfma_f32_16x16x32_bf16 v[24:27], v[162:165], v[212:215], v[24:27]
	v_mfma_f32_16x16x32_bf16 v[20:23], v[188:191], v[212:215], v[20:23]
	v_mfma_f32_16x16x32_bf16 v[8:11], v[162:165], v[220:223], v[8:11]
	v_mfma_f32_16x16x32_bf16 v[4:7], v[188:191], v[220:223], v[4:7]
	s_barrier
	s_add_i32 s63, s63, 2
	s_add_u32 s61, s61, 0x100
	s_addc_u32 s62, s62, 0
	s_add_u32 s0, s0, 0x100
	s_addc_u32 s1, s1, 0
	s_cmp_gt_u32 s63, 29
	s_cbranch_scc0 .LBB0_563
	s_and_b64 vcc, exec, s[34:35]
	s_cbranch_vccz .LBB0_566
	s_barrier

; #define PG8_STAGE(bufoff, gbase, voff) do { _Pragma("unroll") for (int _i = 0; _i < 2; ++_i) \
;         __builtin_amdgcn_global_load_lds((const unsigned*)((const char*)(gbase) + (voff)[_i]), (PG8_LAS unsigned*)(lds + (bufoff) + ldsw + _i * 8192), 16, 0, 0); } while (0)
; #define PG8_LDA(dst, b, h) do { _Pragma("unroll") for (int m = 0; m < 4; ++m) _Pragma("unroll") for (int k = 0; k < 2; ++k) dst[m][k] = *(const PG8_LAS bf16x8*)(lds + PG8_SA(b, h) + aoff + m * 2048 + k * 1024); } while (0)
; #define PG8_LDB(dst, b, h) do { _Pragma("unroll") for (int n = 0; n < 2; ++n) _Pragma("unroll") for (int k = 0; k < 2; ++k) dst[n][k] = *(const PG8_LAS bf16x8*)(lds + PG8_SB(b, h) + boff + n * 2048 + k * 1024); } while (0)
; #define PG8_MMA(ai, bj, At, Bt) do { __builtin_amdgcn_s_setprio(1); _Pragma("unroll") for (int m = 0; m < 4; ++m) _Pragma("unroll") for (int n = 0; n < 2; ++n) _Pragma("unroll") for (int k = 0; k < 2; ++k) \
;         acc[ai][bj][m][n] = __builtin_amdgcn_mfma_f32_16x16x32_bf16(Bt[n][k], At[m][k], acc[ai][bj][m][n], 0, 0, 0); __builtin_amdgcn_s_setprio(0); } while (0)
; #define PG8_WAIT_V(n) asm volatile("s_waitcnt vmcnt(" #n ")" ::: "memory")
; #define PG8_WAIT_L(n) asm volatile("s_waitcnt lgkmcnt(" #n ")" ::: "memory")
; #define PG8_BAR __builtin_amdgcn_s_barrier()
; #define PG8_SCHED __builtin_amdgcn_sched_barrier(0)
; template <class Epi, class Sched, bool ALIGN_EPI = false, bool SP2 = false>
; __device__ __forceinline__ void gemm_phase(PG8_LAS unsigned char* lds, const Gemm g, const Sched& S, const Epi& E) {
;     ...
;             PG8_LDB(B0, 0, 0); PG8_LDB(B1, 0, 1); PG8_SCHED; PG8_LDA(At, 0, 0); PG8_STAGE(PG8_SA(1, 1), a1 + hstep, voffA);
;             PG8_WAIT_V(8); PG8_WAIT_L(0); PG8_BAR; PG8_MMA(0, 0, At, B0); PG8_MMA(0, 1, At, B1); PG8_BAR; PG8_SCHED;
;             PG8_LDA(At, 0, 1); PG8_STAGE(PG8_SB(0, 0), b2, voffB); PG8_STAGE(PG8_SB(0, 1), b2 + hstep, voffB); PG8_STAGE(PG8_SA(0, 0), a2, voffA);
;             PG8_WAIT_V(8); PG8_WAIT_L(0); PG8_BAR; PG8_MMA(1, 0, At, B0); PG8_MMA(1, 1, At, B1); PG8_BAR; PG8_SCHED;
.Lprio_done_660:
.LBB0_660:
	s_add_u32 s14, s0, 0xfff80080
	s_addc_u32 s15, s1, -1
	s_add_i32 s46, 0, 0x10000
	s_cmp_eq_u32 s45, 28
	s_cselect_b32 s17, s23, s15
	s_cselect_b32 s16, s24, s14
	s_cselect_b32 s15, s25, s44
	s_cselect_b32 s14, s42, s43
	s_add_i32 s63, 0, 0x14000
	v_add_u32_e32 v48, s46, v243
	v_add_u32_e32 v96, s63, v243
	ds_read_b128 v[36:39], v48
	ds_read_b128 v[40:43], v48 offset:1024
	ds_read_b128 v[44:47], v48 offset:2048
	ds_read_b128 v[48:51], v48 offset:3072
	ds_read_b128 v[76:79], v96
	ds_read_b128 v[80:83], v96 offset:1024
	ds_read_b128 v[84:87], v96 offset:2048
	ds_read_b128 v[96:99], v96 offset:3072
	v_lshl_add_u64 v[224:225], s[0:1], 0, v[198:199]
	s_add_i32 m0, s29, 0xc000
	ds_read_b128 v[164:167], v249
	ds_read_b128 v[168:171], v249 offset:1024
	ds_read_b128 v[200:203], v249 offset:2048
	ds_read_b128 v[204:207], v249 offset:3072
	ds_read_b128 v[208:211], v249 offset:4096
	ds_read_b128 v[212:215], v249 offset:5120
	ds_read_b128 v[216:219], v249 offset:6144
	ds_read_b128 v[220:223], v249 offset:7168
	global_load_lds_dwordx4 v[224:225], off
	v_lshl_add_u64 v[224:225], s[0:1], 0, v[196:197]
	s_add_i32 m0, s29, 0xe000
	s_nop 0
	global_load_lds_dwordx4 v[224:225], off
	s_waitcnt vmcnt(8)
	s_barrier
	s_waitcnt lgkmcnt(0)
	v_mfma_f32_16x16x32_bf16 v[152:155], v[36:39], v[164:167], v[152:155]
	v_mfma_f32_16x16x32_bf16 v[148:151], v[44:47], v[164:167], v[148:151]
	v_mfma_f32_16x16x32_bf16 v[136:139], v[36:39], v[200:203], v[136:139]
	v_mfma_f32_16x16x32_bf16 v[132:135], v[44:47], v[200:203], v[132:135]
	v_mfma_f32_16x16x32_bf16 v[128:131], v[36:39], v[208:211], v[128:131]
	v_mfma_f32_16x16x32_bf16 v[124:127], v[44:47], v[208:211], v[124:127]
	v_mfma_f32_16x16x32_bf16 v[160:163], v[36:39], v[216:219], v[160:163]
	v_mfma_f32_16x16x32_bf16 v[156:159], v[44:47], v[216:219], v[156:159]
	v_mfma_f32_16x16x32_bf16 v[152:155], v[40:43], v[168:171], v[152:155]
	v_mfma_f32_16x16x32_bf16 v[148:151], v[48:51], v[168:171], v[148:151]
	v_mfma_f32_16x16x32_bf16 v[136:139], v[40:43], v[204:207], v[136:139]
	v_mfma_f32_16x16x32_bf16 v[132:135], v[48:51], v[204:207], v[132:135]
	v_mfma_f32_16x16x32_bf16 v[128:131], v[40:43], v[212:215], v[128:131]
	v_mfma_f32_16x16x32_bf16 v[124:127], v[48:51], v[212:215], v[124:127]
	v_mfma_f32_16x16x32_bf16 v[160:163], v[40:43], v[220:223], v[160:163]
	v_mfma_f32_16x16x32_bf16 v[156:159], v[48:51], v[220:223], v[156:159]
	v_mfma_f32_16x16x32_bf16 v[144:147], v[76:79], v[164:167], v[144:147]
	v_mfma_f32_16x16x32_bf16 v[140:143], v[84:87], v[164:167], v[140:143]
	v_mfma_f32_16x16x32_bf16 v[120:123], v[76:79], v[200:203], v[120:123]
	v_mfma_f32_16x16x32_bf16 v[116:119], v[84:87], v[200:203], v[116:119]
	v_mfma_f32_16x16x32_bf16 v[112:115], v[76:79], v[208:211], v[112:115]
	v_mfma_f32_16x16x32_bf16 v[108:111], v[84:87], v[208:211], v[108:111]
	v_mfma_f32_16x16x32_bf16 v[104:107], v[76:79], v[216:219], v[104:107]
	v_mfma_f32_16x16x32_bf16 v[100:103], v[84:87], v[216:219], v[100:103]
	v_mfma_f32_16x16x32_bf16 v[144:147], v[80:83], v[168:171], v[144:147]
	v_mfma_f32_16x16x32_bf16 v[140:143], v[96:99], v[168:171], v[140:143]
	v_mfma_f32_16x16x32_bf16 v[120:123], v[80:83], v[204:207], v[120:123]
	v_mfma_f32_16x16x32_bf16 v[116:119], v[96:99], v[204:207], v[116:119]
	v_mfma_f32_16x16x32_bf16 v[112:115], v[80:83], v[212:215], v[112:115]
	v_mfma_f32_16x16x32_bf16 v[108:111], v[96:99], v[212:215], v[108:111]
	v_mfma_f32_16x16x32_bf16 v[104:107], v[80:83], v[220:223], v[104:107]
	v_mfma_f32_16x16x32_bf16 v[100:103], v[96:99], v[220:223], v[100:103]
	s_barrier
	s_add_i32 s46, s46, s28
	v_lshl_add_u64 v[232:233], s[14:15], 0, v[188:189]
	s_mov_b32 m0, s46
	ds_read_b128 v[164:167], v249 offset:16384
	ds_read_b128 v[168:171], v249 offset:17408
	ds_read_b128 v[200:203], v249 offset:18432
	ds_read_b128 v[204:207], v249 offset:19456
	ds_read_b128 v[208:211], v249 offset:20480
	ds_read_b128 v[212:215], v249 offset:21504
	ds_read_b128 v[216:219], v249 offset:22528
	ds_read_b128 v[220:223], v249 offset:23552
	global_load_lds_dwordx4 v[232:233], off
	s_add_i32 m0, s46, 0x2000
	s_add_u32 s46, s14, 0x80000
	v_lshl_add_u64 v[234:235], s[14:15], 0, v[184:185]
	s_addc_u32 s47, s15, 0
	s_add_i32 s63, s63, s28
	global_load_lds_dwordx4 v[234:235], off
	v_lshl_add_u64 v[224:225], s[46:47], 0, v[188:189]
	s_mov_b32 m0, s63
	v_lshl_add_u64 v[236:237], s[16:17], 0, v[190:191]
	global_load_lds_dwordx4 v[224:225], off
	v_lshl_add_u64 v[224:225], s[46:47], 0, v[184:185]
	s_add_i32 m0, s63, 0x2000
	v_lshl_add_u64 v[250:251], s[16:17], 0, v[186:187]
	global_load_lds_dwordx4 v[224:225], off
	s_mov_b32 m0, s29
	s_nop 0
	global_load_lds_dwordx4 v[236:237], off
	s_mov_b32 m0, s30
	s_nop 0
	global_load_lds_dwordx4 v[250:251], off
	s_waitcnt vmcnt(8)
	s_barrier
; #define PG8_STAGE(bufoff, gbase, voff) do { _Pragma("unroll") for (int _i = 0; _i < 2; ++_i) \
;         __builtin_amdgcn_global_load_lds((const unsigned*)((const char*)(gbase) + (voff)[_i]), (PG8_LAS unsigned*)(lds + (bufoff) + ldsw + _i * 8192), 16, 0, 0); } while (0)
; #define PG8_LDA(dst, b, h) do { _Pragma("unroll") for (int m = 0; m < 4; ++m) _Pragma("unroll") for (int k = 0; k < 2; ++k) dst[m][k] = *(const PG8_LAS bf16x8*)(lds + PG8_SA(b, h) + aoff + m * 2048 + k * 1024); } while (0)
; #define PG8_LDB(dst, b, h) do { _Pragma("unroll") for (int n = 0; n < 2; ++n) _Pragma("unroll") for (int k = 0; k < 2; ++k) dst[n][k] = *(const PG8_LAS bf16x8*)(lds + PG8_SB(b, h) + boff + n * 2048 + k * 1024); } while (0)
; #define PG8_MMA(ai, bj, At, Bt) do { __builtin_amdgcn_s_setprio(1); _Pragma("unroll") for (int m = 0; m < 4; ++m) _Pragma("unroll") for (int n = 0; n < 2; ++n) _Pragma("unroll") for (int k = 0; k < 2; ++k) \
;         acc[ai][bj][m][n] = __builtin_amdgcn_mfma_f32_16x16x32_bf16(Bt[n][k], At[m][k], acc[ai][bj][m][n], 0, 0, 0); __builtin_amdgcn_s_setprio(0); } while (0)
; #define PG8_WAIT_V(n) asm volatile("s_waitcnt vmcnt(" #n ")" ::: "memory")
; #define PG8_WAIT_L(n) asm volatile("s_waitcnt lgkmcnt(" #n ")" ::: "memory")
; #define PG8_BAR __builtin_amdgcn_s_barrier()
; #define PG8_SCHED __builtin_amdgcn_sched_barrier(0)
; template <class Epi, class Sched, bool ALIGN_EPI = false, bool SP2 = false>
; __device__ __forceinline__ void gemm_phase(PG8_LAS unsigned char* lds, const Gemm g, const Sched& S, const Epi& E) {
;     ...
;             PG8_WAIT_V(8); PG8_WAIT_L(0); PG8_BAR; PG8_MMA(1, 0, At, B0); PG8_MMA(1, 1, At, B1); PG8_BAR; PG8_SCHED;
;             PG8_LDB(B0, 1, 0); PG8_LDB(B1, 1, 1); PG8_SCHED; PG8_LDA(At, 1, 0); PG8_STAGE(PG8_SA(0, 1), a2 + hstep, voffA);
;             PG8_WAIT_V(8); PG8_WAIT_L(0); PG8_BAR; PG8_MMA(0, 0, At, B0); PG8_MMA(0, 1, At, B1); PG8_BAR; PG8_SCHED;
	s_waitcnt lgkmcnt(0)
	v_mfma_f32_16x16x32_bf16 v[72:75], v[36:39], v[164:167], v[72:75]
	v_mfma_f32_16x16x32_bf16 v[68:71], v[44:47], v[164:167], v[68:71]
	v_mfma_f32_16x16x32_bf16 v[64:67], v[36:39], v[200:203], v[64:67]
	v_mfma_f32_16x16x32_bf16 v[60:63], v[44:47], v[200:203], v[60:63]
	v_mfma_f32_16x16x32_bf16 v[56:59], v[36:39], v[208:211], v[56:59]
	v_mfma_f32_16x16x32_bf16 v[52:55], v[44:47], v[208:211], v[52:55]
	v_mfma_f32_16x16x32_bf16 v[36:39], v[36:39], v[216:219], v[92:95]
	v_mfma_f32_16x16x32_bf16 v[72:75], v[40:43], v[168:171], v[72:75]
	v_mfma_f32_16x16x32_bf16 v[68:71], v[48:51], v[168:171], v[68:71]
	v_mfma_f32_16x16x32_bf16 v[64:67], v[40:43], v[204:207], v[64:67]
	v_mfma_f32_16x16x32_bf16 v[60:63], v[48:51], v[204:207], v[60:63]
	v_mfma_f32_16x16x32_bf16 v[56:59], v[40:43], v[212:215], v[56:59]
	v_mfma_f32_16x16x32_bf16 v[52:55], v[48:51], v[212:215], v[52:55]
	v_mfma_f32_16x16x32_bf16 v[36:39], v[40:43], v[220:223], v[36:39]
	v_mfma_f32_16x16x32_bf16 v[40:43], v[44:47], v[216:219], v[88:91]
	v_mfma_f32_16x16x32_bf16 v[40:43], v[48:51], v[220:223], v[40:43]
	v_mfma_f32_16x16x32_bf16 v[32:35], v[76:79], v[164:167], v[32:35]
	v_mfma_f32_16x16x32_bf16 v[28:31], v[84:87], v[164:167], v[28:31]
	v_mfma_f32_16x16x32_bf16 v[24:27], v[76:79], v[200:203], v[24:27]
	v_mfma_f32_16x16x32_bf16 v[20:23], v[84:87], v[200:203], v[20:23]
	v_mfma_f32_16x16x32_bf16 v[16:19], v[76:79], v[208:211], v[16:19]
	v_mfma_f32_16x16x32_bf16 v[12:15], v[84:87], v[208:211], v[12:15]
	v_mfma_f32_16x16x32_bf16 v[8:11], v[76:79], v[216:219], v[8:11]
	v_mfma_f32_16x16x32_bf16 v[4:7], v[84:87], v[216:219], v[4:7]
	v_mfma_f32_16x16x32_bf16 v[32:35], v[80:83], v[168:171], v[32:35]
	v_mfma_f32_16x16x32_bf16 v[28:31], v[96:99], v[168:171], v[28:31]
	v_mfma_f32_16x16x32_bf16 v[24:27], v[80:83], v[204:207], v[24:27]
	v_mfma_f32_16x16x32_bf16 v[20:23], v[96:99], v[204:207], v[20:23]
	v_mfma_f32_16x16x32_bf16 v[16:19], v[80:83], v[212:215], v[16:19]
	v_mfma_f32_16x16x32_bf16 v[12:15], v[96:99], v[212:215], v[12:15]
	v_mfma_f32_16x16x32_bf16 v[8:11], v[80:83], v[220:223], v[8:11]
	v_mfma_f32_16x16x32_bf16 v[4:7], v[96:99], v[220:223], v[4:7]
	s_barrier
	s_add_i32 s46, 0, 0x18000
	s_add_i32 s47, 0, 0x1c000
	v_add_u32_e32 v80, s46, v243
	v_add_u32_e32 v88, s47, v243
	ds_read_b128 v[44:47], v80
	ds_read_b128 v[48:51], v80 offset:1024
	ds_read_b128 v[76:79], v80 offset:2048
	ds_read_b128 v[80:83], v80 offset:3072
	ds_read_b128 v[84:87], v88
	ds_read_b128 v[96:99], v88 offset:1024
	ds_read_b128 v[164:167], v88 offset:2048
	ds_read_b128 v[168:171], v88 offset:3072
	s_add_u32 s16, s16, 0x80000
	s_addc_u32 s17, s17, 0
	s_mov_b32 m0, s31
	v_lshl_add_u64 v[224:225], s[16:17], 0, v[190:191]
	ds_read_b128 v[88:91], v249 offset:32768
	ds_read_b128 v[92:95], v249 offset:33792
	ds_read_b128 v[200:203], v249 offset:34816
	ds_read_b128 v[204:207], v249 offset:35840
	ds_read_b128 v[208:211], v249 offset:36864
	ds_read_b128 v[212:215], v249 offset:37888
	ds_read_b128 v[216:219], v249 offset:38912
	ds_read_b128 v[220:223], v249 offset:39936
	global_load_lds_dwordx4 v[224:225], off
	v_lshl_add_u64 v[224:225], s[16:17], 0, v[186:187]
	s_mov_b32 m0, s34
	s_nop 0
	global_load_lds_dwordx4 v[224:225], off
	s_waitcnt vmcnt(8)
	s_barrier
	s_waitcnt lgkmcnt(0)
	v_mfma_f32_16x16x32_bf16 v[152:155], v[44:47], v[88:91], v[152:155]
	v_mfma_f32_16x16x32_bf16 v[148:151], v[76:79], v[88:91], v[148:151]
	v_mfma_f32_16x16x32_bf16 v[136:139], v[44:47], v[200:203], v[136:139]
	v_mfma_f32_16x16x32_bf16 v[132:135], v[76:79], v[200:203], v[132:135]
	v_mfma_f32_16x16x32_bf16 v[128:131], v[44:47], v[208:211], v[128:131]
	v_mfma_f32_16x16x32_bf16 v[124:127], v[76:79], v[208:211], v[124:127]
	v_mfma_f32_16x16x32_bf16 v[160:163], v[44:47], v[216:219], v[160:163]
	v_mfma_f32_16x16x32_bf16 v[156:159], v[76:79], v[216:219], v[156:159]
	v_mfma_f32_16x16x32_bf16 v[152:155], v[48:51], v[92:95], v[152:155]
	v_mfma_f32_16x16x32_bf16 v[148:151], v[80:83], v[92:95], v[148:151]
	v_mfma_f32_16x16x32_bf16 v[136:139], v[48:51], v[204:207], v[136:139]
	v_mfma_f32_16x16x32_bf16 v[132:135], v[80:83], v[204:207], v[132:135]
	v_mfma_f32_16x16x32_bf16 v[128:131], v[48:51], v[212:215], v[128:131]
	v_mfma_f32_16x16x32_bf16 v[124:127], v[80:83], v[212:215], v[124:127]
	v_mfma_f32_16x16x32_bf16 v[160:163], v[48:51], v[220:223], v[160:163]
	v_mfma_f32_16x16x32_bf16 v[156:159], v[80:83], v[220:223], v[156:159]
	v_mfma_f32_16x16x32_bf16 v[144:147], v[84:87], v[88:91], v[144:147]
	v_mfma_f32_16x16x32_bf16 v[88:91], v[164:167], v[88:91], v[140:143]
	v_mfma_f32_16x16x32_bf16 v[140:143], v[168:171], v[92:95], v[88:91]
	v_mfma_f32_16x16x32_bf16 v[88:91], v[84:87], v[200:203], v[120:123]
	v_mfma_f32_16x16x32_bf16 v[120:123], v[96:99], v[204:207], v[88:91]
	v_mfma_f32_16x16x32_bf16 v[88:91], v[164:167], v[200:203], v[116:119]
	v_mfma_f32_16x16x32_bf16 v[116:119], v[168:171], v[204:207], v[88:91]
	v_mfma_f32_16x16x32_bf16 v[88:91], v[84:87], v[208:211], v[112:115]
	v_mfma_f32_16x16x32_bf16 v[112:115], v[96:99], v[212:215], v[88:91]
	v_mfma_f32_16x16x32_bf16 v[88:91], v[164:167], v[208:211], v[108:111]
	v_mfma_f32_16x16x32_bf16 v[108:111], v[168:171], v[212:215], v[88:91]
	v_mfma_f32_16x16x32_bf16 v[88:91], v[84:87], v[216:219], v[104:107]
	v_mfma_f32_16x16x32_bf16 v[104:107], v[96:99], v[220:223], v[88:91]
	v_mfma_f32_16x16x32_bf16 v[88:91], v[164:167], v[216:219], v[100:103]
	v_mfma_f32_16x16x32_bf16 v[144:147], v[96:99], v[92:95], v[144:147]
	v_mfma_f32_16x16x32_bf16 v[100:103], v[168:171], v[220:223], v[88:91]
	s_barrier
; #define PG8_STAGE(bufoff, gbase, voff) do { _Pragma("unroll") for (int _i = 0; _i < 2; ++_i) \
;         __builtin_amdgcn_global_load_lds((const unsigned*)((const char*)(gbase) + (voff)[_i]), (PG8_LAS unsigned*)(lds + (bufoff) + ldsw + _i * 8192), 16, 0, 0); } while (0)
; #define PG8_LDA(dst, b, h) do { _Pragma("unroll") for (int m = 0; m < 4; ++m) _Pragma("unroll") for (int k = 0; k < 2; ++k) dst[m][k] = *(const PG8_LAS bf16x8*)(lds + PG8_SA(b, h) + aoff + m * 2048 + k * 1024); } while (0)
; #define PG8_MMA(ai, bj, At, Bt) do { __builtin_amdgcn_s_setprio(1); _Pragma("unroll") for (int m = 0; m < 4; ++m) _Pragma("unroll") for (int n = 0; n < 2; ++n) _Pragma("unroll") for (int k = 0; k < 2; ++k) \
;         acc[ai][bj][m][n] = __builtin_amdgcn_mfma_f32_16x16x32_bf16(Bt[n][k], At[m][k], acc[ai][bj][m][n], 0, 0, 0); __builtin_amdgcn_s_setprio(0); } while (0)
; #define PG8_WAIT_V(n) asm volatile("s_waitcnt vmcnt(" #n ")" ::: "memory")
; #define PG8_WAIT_L(n) asm volatile("s_waitcnt lgkmcnt(" #n ")" ::: "memory")
; #define PG8_BAR __builtin_amdgcn_s_barrier()
; #define PG8_SCHED __builtin_amdgcn_sched_barrier(0)
; template <class Epi, class Sched, bool ALIGN_EPI = false, bool SP2 = false>
; __device__ __forceinline__ void gemm_phase(PG8_LAS unsigned char* lds, const Gemm g, const Sched& S, const Epi& E) {
;     ...
;         for (int t = 0; t < nt; t += 2) {
;             const bool last = (t == nt - 2);
;     ...
;             PG8_LDA(At, 1, 1); PG8_STAGE(PG8_SB(1, 0), b3, voffB); PG8_STAGE(PG8_SB(1, 1), b3 + hstep, voffB); PG8_STAGE(PG8_SA(1, 0), a3, voffA);
;             PG8_WAIT_V(8); PG8_WAIT_L(0); PG8_BAR; PG8_MMA(1, 0, At, B0); PG8_MMA(1, 1, At, B1); PG8_BAR; PG8_SCHED;
	s_add_i32 s16, s46, s28
	s_nop 2
	v_lshl_add_u64 v[88:89], v[232:233], 0, s[10:11]
	s_mov_b32 m0, s16
	ds_read_b128 v[200:203], v249 offset:49152
	ds_read_b128 v[204:207], v249 offset:50176
	ds_read_b128 v[208:211], v249 offset:51200
	ds_read_b128 v[212:215], v249 offset:52224
	ds_read_b128 v[216:219], v249 offset:53248
	ds_read_b128 v[220:223], v249 offset:54272
	ds_read_b128 v[224:227], v249 offset:55296
	ds_read_b128 v[228:231], v249 offset:56320
	global_load_lds_dwordx4 v[88:89], off
	s_add_i32 m0, s16, 0x2000
	s_add_u32 s14, s14, 0x80080
	v_lshl_add_u64 v[88:89], v[234:235], 0, s[10:11]
	s_addc_u32 s15, s15, 0
	s_add_i32 s16, s47, s28
	global_load_lds_dwordx4 v[88:89], off
	v_lshl_add_u64 v[88:89], s[14:15], 0, v[188:189]
	s_mov_b32 m0, s16
	s_nop 0
	global_load_lds_dwordx4 v[88:89], off
	v_lshl_add_u64 v[88:89], s[14:15], 0, v[184:185]
	s_add_i32 m0, s16, 0x2000
	s_nop 0
	global_load_lds_dwordx4 v[88:89], off
	v_lshl_add_u64 v[88:89], v[236:237], 0, s[10:11]
	s_mov_b32 m0, s72
	s_nop 0
	global_load_lds_dwordx4 v[88:89], off
	v_lshl_add_u64 v[88:89], v[250:251], 0, s[10:11]
	s_mov_b32 m0, s73
	s_nop 0
	global_load_lds_dwordx4 v[88:89], off
	s_waitcnt vmcnt(8)
	s_barrier
	s_waitcnt lgkmcnt(0)
	v_mfma_f32_16x16x32_bf16 v[36:39], v[44:47], v[224:227], v[36:39]
	v_mfma_f32_16x16x32_bf16 v[72:75], v[44:47], v[200:203], v[72:75]
	v_mfma_f32_16x16x32_bf16 v[68:71], v[76:79], v[200:203], v[68:71]
	v_mfma_f32_16x16x32_bf16 v[64:67], v[44:47], v[208:211], v[64:67]
	v_mfma_f32_16x16x32_bf16 v[60:63], v[76:79], v[208:211], v[60:63]
	v_mfma_f32_16x16x32_bf16 v[56:59], v[44:47], v[216:219], v[56:59]
	v_mfma_f32_16x16x32_bf16 v[52:55], v[76:79], v[216:219], v[52:55]
	v_mfma_f32_16x16x32_bf16 v[92:95], v[48:51], v[228:231], v[36:39]
	v_mfma_f32_16x16x32_bf16 v[36:39], v[76:79], v[224:227], v[40:43]
	v_mfma_f32_16x16x32_bf16 v[72:75], v[48:51], v[204:207], v[72:75]
	v_mfma_f32_16x16x32_bf16 v[68:71], v[80:83], v[204:207], v[68:71]
	v_mfma_f32_16x16x32_bf16 v[64:67], v[48:51], v[212:215], v[64:67]
	v_mfma_f32_16x16x32_bf16 v[60:63], v[80:83], v[212:215], v[60:63]
	v_mfma_f32_16x16x32_bf16 v[56:59], v[48:51], v[220:223], v[56:59]
	v_mfma_f32_16x16x32_bf16 v[52:55], v[80:83], v[220:223], v[52:55]
	v_mfma_f32_16x16x32_bf16 v[88:91], v[80:83], v[228:231], v[36:39]
	v_mfma_f32_16x16x32_bf16 v[32:35], v[84:87], v[200:203], v[32:35]
	v_mfma_f32_16x16x32_bf16 v[28:31], v[164:167], v[200:203], v[28:31]
	v_mfma_f32_16x16x32_bf16 v[24:27], v[84:87], v[208:211], v[24:27]
	v_mfma_f32_16x16x32_bf16 v[20:23], v[164:167], v[208:211], v[20:23]
	v_mfma_f32_16x16x32_bf16 v[16:19], v[84:87], v[216:219], v[16:19]
	v_mfma_f32_16x16x32_bf16 v[12:15], v[164:167], v[216:219], v[12:15]
	v_mfma_f32_16x16x32_bf16 v[8:11], v[84:87], v[224:227], v[8:11]
	v_mfma_f32_16x16x32_bf16 v[4:7], v[164:167], v[224:227], v[4:7]
	v_mfma_f32_16x16x32_bf16 v[32:35], v[96:99], v[204:207], v[32:35]
	v_mfma_f32_16x16x32_bf16 v[28:31], v[168:171], v[204:207], v[28:31]
	v_mfma_f32_16x16x32_bf16 v[24:27], v[96:99], v[212:215], v[24:27]
	v_mfma_f32_16x16x32_bf16 v[20:23], v[168:171], v[212:215], v[20:23]
	v_mfma_f32_16x16x32_bf16 v[16:19], v[96:99], v[220:223], v[16:19]
	v_mfma_f32_16x16x32_bf16 v[12:15], v[168:171], v[220:223], v[12:15]
	v_mfma_f32_16x16x32_bf16 v[8:11], v[96:99], v[228:231], v[8:11]
	v_mfma_f32_16x16x32_bf16 v[4:7], v[168:171], v[228:231], v[4:7]
	s_barrier
	s_add_i32 s45, s45, 2
	s_add_u32 s43, s43, 0x100
	s_addc_u32 s44, s44, 0
	s_add_u32 s0, s0, 0x100
	s_addc_u32 s1, s1, 0
	s_cmp_gt_u32 s45, 29
	s_cbranch_scc0 .LBB0_660
	s_and_b64 vcc, exec, s[52:53]
	s_cbranch_vccz .LBB0_663
	s_barrier

; #define PG8_STAGE(bufoff, gbase, voff) do { _Pragma("unroll") for (int _i = 0; _i < 2; ++_i) \
;         __builtin_amdgcn_global_load_lds((const unsigned*)((const char*)(gbase) + (voff)[_i]), (PG8_LAS unsigned*)(lds + (bufoff) + ldsw + _i * 8192), 16, 0, 0); } while (0)
; #define PG8_LDA(dst, b, h) do { _Pragma("unroll") for (int m = 0; m < 4; ++m) _Pragma("unroll") for (int k = 0; k < 2; ++k) dst[m][k] = *(const PG8_LAS bf16x8*)(lds + PG8_SA(b, h) + aoff + m * 2048 + k * 1024); } while (0)
; #define PG8_LDB(dst, b, h) do { _Pragma("unroll") for (int n = 0; n < 2; ++n) _Pragma("unroll") for (int k = 0; k < 2; ++k) dst[n][k] = *(const PG8_LAS bf16x8*)(lds + PG8_SB(b, h) + boff + n * 2048 + k * 1024); } while (0)
; #define PG8_MMA(ai, bj, At, Bt) do { __builtin_amdgcn_s_setprio(1); _Pragma("unroll") for (int m = 0; m < 4; ++m) _Pragma("unroll") for (int n = 0; n < 2; ++n) _Pragma("unroll") for (int k = 0; k < 2; ++k) \
;         acc[ai][bj][m][n] = __builtin_amdgcn_mfma_f32_16x16x32_bf16(Bt[n][k], At[m][k], acc[ai][bj][m][n], 0, 0, 0); __builtin_amdgcn_s_setprio(0); } while (0)
; #define PG8_WAIT_V(n) asm volatile("s_waitcnt vmcnt(" #n ")" ::: "memory")
; #define PG8_WAIT_L(n) asm volatile("s_waitcnt lgkmcnt(" #n ")" ::: "memory")
; #define PG8_BAR __builtin_amdgcn_s_barrier()
; #define PG8_SCHED __builtin_amdgcn_sched_barrier(0)
; template <class Epi, class Sched, bool ALIGN_EPI = false, bool SP2 = false>
; __device__ __forceinline__ void gemm_phase(PG8_LAS unsigned char* lds, const Gemm g, const Sched& S, const Epi& E) {
;     ...
;             PG8_LDB(B0, 0, 0); PG8_LDB(B1, 0, 1); PG8_SCHED; PG8_LDA(At, 0, 0); PG8_STAGE(PG8_SA(1, 1), a1 + hstep, voffA);
;             PG8_WAIT_V(8); PG8_WAIT_L(0); PG8_BAR; PG8_MMA(0, 0, At, B0); PG8_MMA(0, 1, At, B1); PG8_BAR; PG8_SCHED;
;             PG8_LDA(At, 0, 1); PG8_STAGE(PG8_SB(0, 0), b2, voffB); PG8_STAGE(PG8_SB(0, 1), b2 + hstep, voffB); PG8_STAGE(PG8_SA(0, 0), a2, voffA);
;             PG8_WAIT_V(8); PG8_WAIT_L(0); PG8_BAR; PG8_MMA(1, 0, At, B0); PG8_MMA(1, 1, At, B1); PG8_BAR; PG8_SCHED;
.Lprio_done_822:
.LBB0_822:
	s_add_u32 s14, s0, 0x100
	s_addc_u32 s15, s1, 0
	s_add_i32 s60, 0, 0x10000
	s_cmpk_eq_i32 s25, 0x52
	s_cselect_b32 s19, s41, s15
	s_cselect_b32 s18, s40, s14
	s_cselect_b32 s17, s51, s24
	s_cselect_b32 s16, s50, s23
	s_add_i32 s61, 0, 0x14000
	v_add_u32_e32 v154, s60, v159
	v_add_u32_e32 v170, s61, v159
	ds_read_b128 v[116:119], v154
	ds_read_b128 v[120:123], v154 offset:1024
	ds_read_b128 v[150:153], v154 offset:2048
	ds_read_b128 v[154:157], v154 offset:3072
	ds_read_b128 v[162:165], v170
	ds_read_b128 v[166:169], v170 offset:1024
	ds_read_b128 v[184:187], v170 offset:2048
	ds_read_b128 v[188:191], v170 offset:3072
	v_lshl_add_u64 v[170:171], s[0:1], 0, v[148:149]
	s_add_i32 m0, s31, 0xc000
	ds_read_b128 v[192:195], v161
	ds_read_b128 v[196:199], v161 offset:1024
	ds_read_b128 v[200:203], v161 offset:2048
	ds_read_b128 v[204:207], v161 offset:3072
	ds_read_b128 v[208:211], v161 offset:4096
	ds_read_b128 v[212:215], v161 offset:5120
	ds_read_b128 v[216:219], v161 offset:6144
	ds_read_b128 v[220:223], v161 offset:7168
	global_load_lds_dwordx4 v[170:171], off
	v_lshl_add_u64 v[170:171], s[0:1], 0, v[146:147]
	s_add_i32 m0, s31, 0xe000
	s_nop 0
	global_load_lds_dwordx4 v[170:171], off
	s_waitcnt vmcnt(8)
	s_barrier
	s_waitcnt lgkmcnt(0)
	v_mfma_f32_16x16x32_bf16 v[136:139], v[116:119], v[192:195], v[136:139]
	v_mfma_f32_16x16x32_bf16 v[132:135], v[150:153], v[192:195], v[132:135]
	v_mfma_f32_16x16x32_bf16 v[112:115], v[116:119], v[200:203], v[112:115]
	v_mfma_f32_16x16x32_bf16 v[108:111], v[150:153], v[200:203], v[108:111]
	v_mfma_f32_16x16x32_bf16 v[96:99], v[116:119], v[208:211], v[96:99]
	v_mfma_f32_16x16x32_bf16 v[92:95], v[150:153], v[208:211], v[92:95]
	v_mfma_f32_16x16x32_bf16 v[80:83], v[116:119], v[216:219], v[80:83]
	v_mfma_f32_16x16x32_bf16 v[76:79], v[150:153], v[216:219], v[76:79]
	v_mfma_f32_16x16x32_bf16 v[136:139], v[120:123], v[196:199], v[136:139]
	v_mfma_f32_16x16x32_bf16 v[132:135], v[154:157], v[196:199], v[132:135]
	v_mfma_f32_16x16x32_bf16 v[112:115], v[120:123], v[204:207], v[112:115]
	v_mfma_f32_16x16x32_bf16 v[108:111], v[154:157], v[204:207], v[108:111]
	v_mfma_f32_16x16x32_bf16 v[96:99], v[120:123], v[212:215], v[96:99]
	v_mfma_f32_16x16x32_bf16 v[92:95], v[154:157], v[212:215], v[92:95]
	v_mfma_f32_16x16x32_bf16 v[80:83], v[120:123], v[220:223], v[80:83]
	v_mfma_f32_16x16x32_bf16 v[76:79], v[154:157], v[220:223], v[76:79]
	v_mfma_f32_16x16x32_bf16 v[128:131], v[162:165], v[192:195], v[128:131]
	v_mfma_f32_16x16x32_bf16 v[124:127], v[184:187], v[192:195], v[124:127]
	v_mfma_f32_16x16x32_bf16 v[104:107], v[162:165], v[200:203], v[104:107]
	v_mfma_f32_16x16x32_bf16 v[100:103], v[184:187], v[200:203], v[100:103]
	v_mfma_f32_16x16x32_bf16 v[88:91], v[162:165], v[208:211], v[88:91]
	v_mfma_f32_16x16x32_bf16 v[84:87], v[184:187], v[208:211], v[84:87]
	v_mfma_f32_16x16x32_bf16 v[72:75], v[162:165], v[216:219], v[72:75]
	v_mfma_f32_16x16x32_bf16 v[68:71], v[184:187], v[216:219], v[68:71]
	v_mfma_f32_16x16x32_bf16 v[128:131], v[166:169], v[196:199], v[128:131]
	v_mfma_f32_16x16x32_bf16 v[124:127], v[188:191], v[196:199], v[124:127]
	v_mfma_f32_16x16x32_bf16 v[104:107], v[166:169], v[204:207], v[104:107]
	v_mfma_f32_16x16x32_bf16 v[100:103], v[188:191], v[204:207], v[100:103]
	v_mfma_f32_16x16x32_bf16 v[88:91], v[166:169], v[212:215], v[88:91]
	v_mfma_f32_16x16x32_bf16 v[84:87], v[188:191], v[212:215], v[84:87]
	v_mfma_f32_16x16x32_bf16 v[72:75], v[166:169], v[220:223], v[72:75]
	v_mfma_f32_16x16x32_bf16 v[68:71], v[188:191], v[220:223], v[68:71]
	s_barrier
	s_add_i32 s0, s60, s30
	v_lshl_add_u64 v[170:171], s[16:17], 0, v[174:175]
	s_mov_b32 m0, s0
	ds_read_b128 v[192:195], v161 offset:16384
	ds_read_b128 v[196:199], v161 offset:17408
	ds_read_b128 v[200:203], v161 offset:18432
	ds_read_b128 v[204:207], v161 offset:19456
	ds_read_b128 v[208:211], v161 offset:20480
	ds_read_b128 v[212:215], v161 offset:21504
	ds_read_b128 v[216:219], v161 offset:22528
	ds_read_b128 v[220:223], v161 offset:23552
	global_load_lds_dwordx4 v[170:171], off
	s_add_i32 m0, s0, 0x2000
	s_add_u32 s0, s16, 0x158000
	v_lshl_add_u64 v[224:225], s[16:17], 0, v[140:141]
	s_addc_u32 s1, s17, 0
	s_add_i32 s60, s61, s30
	global_load_lds_dwordx4 v[224:225], off
	v_lshl_add_u64 v[226:227], s[0:1], 0, v[174:175]
	s_mov_b32 m0, s60
	v_lshl_add_u64 v[228:229], s[18:19], 0, v[142:143]
	global_load_lds_dwordx4 v[226:227], off
	v_lshl_add_u64 v[226:227], s[0:1], 0, v[140:141]
	s_add_i32 m0, s60, 0x2000
	s_nop 0
	global_load_lds_dwordx4 v[226:227], off
	v_lshl_add_u64 v[226:227], s[18:19], 0, v[144:145]
	s_mov_b32 m0, s31
	s_nop 0
	global_load_lds_dwordx4 v[226:227], off
	s_mov_b32 m0, s34
	s_nop 0
	global_load_lds_dwordx4 v[228:229], off
	s_waitcnt vmcnt(8)
	s_barrier
; #define PG8_STAGE(bufoff, gbase, voff) do { _Pragma("unroll") for (int _i = 0; _i < 2; ++_i) \
;         __builtin_amdgcn_global_load_lds((const unsigned*)((const char*)(gbase) + (voff)[_i]), (PG8_LAS unsigned*)(lds + (bufoff) + ldsw + _i * 8192), 16, 0, 0); } while (0)
; #define PG8_LDA(dst, b, h) do { _Pragma("unroll") for (int m = 0; m < 4; ++m) _Pragma("unroll") for (int k = 0; k < 2; ++k) dst[m][k] = *(const PG8_LAS bf16x8*)(lds + PG8_SA(b, h) + aoff + m * 2048 + k * 1024); } while (0)
; #define PG8_LDB(dst, b, h) do { _Pragma("unroll") for (int n = 0; n < 2; ++n) _Pragma("unroll") for (int k = 0; k < 2; ++k) dst[n][k] = *(const PG8_LAS bf16x8*)(lds + PG8_SB(b, h) + boff + n * 2048 + k * 1024); } while (0)
; #define PG8_MMA(ai, bj, At, Bt) do { __builtin_amdgcn_s_setprio(1); _Pragma("unroll") for (int m = 0; m < 4; ++m) _Pragma("unroll") for (int n = 0; n < 2; ++n) _Pragma("unroll") for (int k = 0; k < 2; ++k) \
;         acc[ai][bj][m][n] = __builtin_amdgcn_mfma_f32_16x16x32_bf16(Bt[n][k], At[m][k], acc[ai][bj][m][n], 0, 0, 0); __builtin_amdgcn_s_setprio(0); } while (0)
; #define PG8_WAIT_V(n) asm volatile("s_waitcnt vmcnt(" #n ")" ::: "memory")
; #define PG8_WAIT_L(n) asm volatile("s_waitcnt lgkmcnt(" #n ")" ::: "memory")
; #define PG8_BAR __builtin_amdgcn_s_barrier()
; #define PG8_SCHED __builtin_amdgcn_sched_barrier(0)
; template <class Epi, class Sched, bool ALIGN_EPI = false, bool SP2 = false>
; __device__ __forceinline__ void gemm_phase(PG8_LAS unsigned char* lds, const Gemm g, const Sched& S, const Epi& E) {
;     ...
;             PG8_WAIT_V(8); PG8_WAIT_L(0); PG8_BAR; PG8_MMA(1, 0, At, B0); PG8_MMA(1, 1, At, B1); PG8_BAR; PG8_SCHED;
;             PG8_LDB(B0, 1, 0); PG8_LDB(B1, 1, 1); PG8_SCHED; PG8_LDA(At, 1, 0); PG8_STAGE(PG8_SA(0, 1), a2 + hstep, voffA);
;             PG8_WAIT_V(8); PG8_WAIT_L(0); PG8_BAR; PG8_MMA(0, 0, At, B0); PG8_MMA(0, 1, At, B1); PG8_BAR; PG8_SCHED;
	s_waitcnt lgkmcnt(0)
	v_mfma_f32_16x16x32_bf16 v[64:67], v[116:119], v[192:195], v[64:67]
	v_mfma_f32_16x16x32_bf16 v[60:63], v[150:153], v[192:195], v[60:63]
	v_mfma_f32_16x16x32_bf16 v[48:51], v[116:119], v[200:203], v[48:51]
	v_mfma_f32_16x16x32_bf16 v[44:47], v[150:153], v[200:203], v[44:47]
	v_mfma_f32_16x16x32_bf16 v[32:35], v[116:119], v[208:211], v[32:35]
	v_mfma_f32_16x16x32_bf16 v[28:31], v[150:153], v[208:211], v[28:31]
	v_mfma_f32_16x16x32_bf16 v[16:19], v[116:119], v[216:219], v[16:19]
	v_mfma_f32_16x16x32_bf16 v[12:15], v[150:153], v[216:219], v[12:15]
	v_mfma_f32_16x16x32_bf16 v[64:67], v[120:123], v[196:199], v[64:67]
	v_mfma_f32_16x16x32_bf16 v[60:63], v[154:157], v[196:199], v[60:63]
	v_mfma_f32_16x16x32_bf16 v[48:51], v[120:123], v[204:207], v[48:51]
	v_mfma_f32_16x16x32_bf16 v[44:47], v[154:157], v[204:207], v[44:47]
	v_mfma_f32_16x16x32_bf16 v[32:35], v[120:123], v[212:215], v[32:35]
	v_mfma_f32_16x16x32_bf16 v[28:31], v[154:157], v[212:215], v[28:31]
	v_mfma_f32_16x16x32_bf16 v[16:19], v[120:123], v[220:223], v[16:19]
	v_mfma_f32_16x16x32_bf16 v[12:15], v[154:157], v[220:223], v[12:15]
	v_mfma_f32_16x16x32_bf16 v[56:59], v[162:165], v[192:195], v[56:59]
	v_mfma_f32_16x16x32_bf16 v[52:55], v[184:187], v[192:195], v[52:55]
	v_mfma_f32_16x16x32_bf16 v[40:43], v[162:165], v[200:203], v[40:43]
	v_mfma_f32_16x16x32_bf16 v[36:39], v[184:187], v[200:203], v[36:39]
	v_mfma_f32_16x16x32_bf16 v[24:27], v[162:165], v[208:211], v[24:27]
	v_mfma_f32_16x16x32_bf16 v[20:23], v[184:187], v[208:211], v[20:23]
	v_mfma_f32_16x16x32_bf16 v[8:11], v[162:165], v[216:219], v[8:11]
	v_mfma_f32_16x16x32_bf16 v[4:7], v[184:187], v[216:219], v[4:7]
	v_mfma_f32_16x16x32_bf16 v[56:59], v[166:169], v[196:199], v[56:59]
	v_mfma_f32_16x16x32_bf16 v[52:55], v[188:191], v[196:199], v[52:55]
	v_mfma_f32_16x16x32_bf16 v[40:43], v[166:169], v[204:207], v[40:43]
	v_mfma_f32_16x16x32_bf16 v[36:39], v[188:191], v[204:207], v[36:39]
	v_mfma_f32_16x16x32_bf16 v[24:27], v[166:169], v[212:215], v[24:27]
	v_mfma_f32_16x16x32_bf16 v[20:23], v[188:191], v[212:215], v[20:23]
	v_mfma_f32_16x16x32_bf16 v[8:11], v[166:169], v[220:223], v[8:11]
	v_mfma_f32_16x16x32_bf16 v[4:7], v[188:191], v[220:223], v[4:7]
	s_barrier
	s_add_i32 s60, 0, 0x18000
	s_add_i32 s61, 0, 0x1c000
	v_add_u32_e32 v154, s60, v159
	v_add_u32_e32 v179, s61, v159
	ds_read_b128 v[116:119], v154
	ds_read_b128 v[120:123], v154 offset:1024
	ds_read_b128 v[150:153], v154 offset:2048
	ds_read_b128 v[154:157], v154 offset:3072
	ds_read_b128 v[162:165], v179
	ds_read_b128 v[166:169], v179 offset:1024
	ds_read_b128 v[184:187], v179 offset:2048
	ds_read_b128 v[188:191], v179 offset:3072
	s_add_u32 s0, s18, 0x158000
	s_addc_u32 s1, s19, 0
	s_mov_b32 m0, s35
	v_lshl_add_u64 v[230:231], s[0:1], 0, v[144:145]
	ds_read_b128 v[192:195], v161 offset:32768
	ds_read_b128 v[196:199], v161 offset:33792
	ds_read_b128 v[200:203], v161 offset:34816
	ds_read_b128 v[204:207], v161 offset:35840
	ds_read_b128 v[208:211], v161 offset:36864
	ds_read_b128 v[212:215], v161 offset:37888
	ds_read_b128 v[216:219], v161 offset:38912
	ds_read_b128 v[220:223], v161 offset:39936
	global_load_lds_dwordx4 v[230:231], off
	v_lshl_add_u64 v[230:231], s[0:1], 0, v[142:143]
	s_mov_b32 m0, s52
	s_nop 0
	global_load_lds_dwordx4 v[230:231], off
	s_waitcnt vmcnt(8)
	s_barrier
	s_waitcnt lgkmcnt(0)
	v_mfma_f32_16x16x32_bf16 v[136:139], v[116:119], v[192:195], v[136:139]
	v_mfma_f32_16x16x32_bf16 v[132:135], v[150:153], v[192:195], v[132:135]
	v_mfma_f32_16x16x32_bf16 v[112:115], v[116:119], v[200:203], v[112:115]
	v_mfma_f32_16x16x32_bf16 v[108:111], v[150:153], v[200:203], v[108:111]
	v_mfma_f32_16x16x32_bf16 v[96:99], v[116:119], v[208:211], v[96:99]
	v_mfma_f32_16x16x32_bf16 v[92:95], v[150:153], v[208:211], v[92:95]
	v_mfma_f32_16x16x32_bf16 v[80:83], v[116:119], v[216:219], v[80:83]
	v_mfma_f32_16x16x32_bf16 v[76:79], v[150:153], v[216:219], v[76:79]
	v_mfma_f32_16x16x32_bf16 v[136:139], v[120:123], v[196:199], v[136:139]
	v_mfma_f32_16x16x32_bf16 v[132:135], v[154:157], v[196:199], v[132:135]
	v_mfma_f32_16x16x32_bf16 v[112:115], v[120:123], v[204:207], v[112:115]
	v_mfma_f32_16x16x32_bf16 v[108:111], v[154:157], v[204:207], v[108:111]
	v_mfma_f32_16x16x32_bf16 v[96:99], v[120:123], v[212:215], v[96:99]
	v_mfma_f32_16x16x32_bf16 v[92:95], v[154:157], v[212:215], v[92:95]
	v_mfma_f32_16x16x32_bf16 v[80:83], v[120:123], v[220:223], v[80:83]
	v_mfma_f32_16x16x32_bf16 v[76:79], v[154:157], v[220:223], v[76:79]
	v_mfma_f32_16x16x32_bf16 v[128:131], v[162:165], v[192:195], v[128:131]
	v_mfma_f32_16x16x32_bf16 v[124:127], v[184:187], v[192:195], v[124:127]
	v_mfma_f32_16x16x32_bf16 v[104:107], v[162:165], v[200:203], v[104:107]
	v_mfma_f32_16x16x32_bf16 v[100:103], v[184:187], v[200:203], v[100:103]
	v_mfma_f32_16x16x32_bf16 v[88:91], v[162:165], v[208:211], v[88:91]
	v_mfma_f32_16x16x32_bf16 v[84:87], v[184:187], v[208:211], v[84:87]
	v_mfma_f32_16x16x32_bf16 v[72:75], v[162:165], v[216:219], v[72:75]
	v_mfma_f32_16x16x32_bf16 v[68:71], v[184:187], v[216:219], v[68:71]
	v_mfma_f32_16x16x32_bf16 v[128:131], v[166:169], v[196:199], v[128:131]
	v_mfma_f32_16x16x32_bf16 v[124:127], v[188:191], v[196:199], v[124:127]
	v_mfma_f32_16x16x32_bf16 v[104:107], v[166:169], v[204:207], v[104:107]
	v_mfma_f32_16x16x32_bf16 v[100:103], v[188:191], v[204:207], v[100:103]
	v_mfma_f32_16x16x32_bf16 v[88:91], v[166:169], v[212:215], v[88:91]
	v_mfma_f32_16x16x32_bf16 v[84:87], v[188:191], v[212:215], v[84:87]
	v_mfma_f32_16x16x32_bf16 v[72:75], v[166:169], v[220:223], v[72:75]
	v_mfma_f32_16x16x32_bf16 v[68:71], v[188:191], v[220:223], v[68:71]
	s_barrier
; #define PG8_STAGE(bufoff, gbase, voff) do { _Pragma("unroll") for (int _i = 0; _i < 2; ++_i) \
;         __builtin_amdgcn_global_load_lds((const unsigned*)((const char*)(gbase) + (voff)[_i]), (PG8_LAS unsigned*)(lds + (bufoff) + ldsw + _i * 8192), 16, 0, 0); } while (0)
; #define PG8_LDA(dst, b, h) do { _Pragma("unroll") for (int m = 0; m < 4; ++m) _Pragma("unroll") for (int k = 0; k < 2; ++k) dst[m][k] = *(const PG8_LAS bf16x8*)(lds + PG8_SA(b, h) + aoff + m * 2048 + k * 1024); } while (0)
; #define PG8_MMA(ai, bj, At, Bt) do { __builtin_amdgcn_s_setprio(1); _Pragma("unroll") for (int m = 0; m < 4; ++m) _Pragma("unroll") for (int n = 0; n < 2; ++n) _Pragma("unroll") for (int k = 0; k < 2; ++k) \
;         acc[ai][bj][m][n] = __builtin_amdgcn_mfma_f32_16x16x32_bf16(Bt[n][k], At[m][k], acc[ai][bj][m][n], 0, 0, 0); __builtin_amdgcn_s_setprio(0); } while (0)
; #define PG8_WAIT_V(n) asm volatile("s_waitcnt vmcnt(" #n ")" ::: "memory")
; #define PG8_WAIT_L(n) asm volatile("s_waitcnt lgkmcnt(" #n ")" ::: "memory")
; #define PG8_BAR __builtin_amdgcn_s_barrier()
; #define PG8_SCHED __builtin_amdgcn_sched_barrier(0)
; template <class Epi, class Sched, bool ALIGN_EPI = false, bool SP2 = false>
; __device__ __forceinline__ void gemm_phase(PG8_LAS unsigned char* lds, const Gemm g, const Sched& S, const Epi& E) {
;     ...
;         for (int t = 0; t < nt; t += 2) {
;             const bool last = (t == nt - 2);
;     ...
;             PG8_LDA(At, 1, 1); PG8_STAGE(PG8_SB(1, 0), b3, voffB); PG8_STAGE(PG8_SB(1, 1), b3 + hstep, voffB); PG8_STAGE(PG8_SA(1, 0), a3, voffA);
;             PG8_WAIT_V(8); PG8_WAIT_L(0); PG8_BAR; PG8_MMA(1, 0, At, B0); PG8_MMA(1, 1, At, B1); PG8_BAR; PG8_SCHED;
	s_add_i32 s0, s60, s30
	v_lshl_add_u64 v[170:171], v[170:171], 0, s[10:11]
	s_mov_b32 m0, s0
	ds_read_b128 v[192:195], v161 offset:49152
	ds_read_b128 v[196:199], v161 offset:50176
	ds_read_b128 v[200:203], v161 offset:51200
	ds_read_b128 v[204:207], v161 offset:52224
	ds_read_b128 v[208:211], v161 offset:53248
	ds_read_b128 v[212:215], v161 offset:54272
	ds_read_b128 v[216:219], v161 offset:55296
	ds_read_b128 v[220:223], v161 offset:56320
	global_load_lds_dwordx4 v[170:171], off
	s_add_i32 m0, s0, 0x2000
	s_add_u32 s0, s16, 0x158080
	v_lshl_add_u64 v[170:171], v[224:225], 0, s[10:11]
	s_addc_u32 s1, s17, 0
	s_add_i32 s16, s61, s30
	global_load_lds_dwordx4 v[170:171], off
	v_lshl_add_u64 v[170:171], s[0:1], 0, v[174:175]
	s_mov_b32 m0, s16
	s_nop 0
	global_load_lds_dwordx4 v[170:171], off
	v_lshl_add_u64 v[170:171], s[0:1], 0, v[140:141]
	s_add_i32 m0, s16, 0x2000
	s_nop 0
	global_load_lds_dwordx4 v[170:171], off
	v_lshl_add_u64 v[170:171], v[226:227], 0, s[10:11]
	s_mov_b32 m0, s54
	s_nop 0
	global_load_lds_dwordx4 v[170:171], off
	v_lshl_add_u64 v[170:171], v[228:229], 0, s[10:11]
	s_mov_b32 m0, s55
	s_nop 0
	global_load_lds_dwordx4 v[170:171], off
	s_waitcnt vmcnt(8)
	s_barrier
	s_waitcnt lgkmcnt(0)
	v_mfma_f32_16x16x32_bf16 v[64:67], v[116:119], v[192:195], v[64:67]
	v_mfma_f32_16x16x32_bf16 v[60:63], v[150:153], v[192:195], v[60:63]
	v_mfma_f32_16x16x32_bf16 v[48:51], v[116:119], v[200:203], v[48:51]
	v_mfma_f32_16x16x32_bf16 v[44:47], v[150:153], v[200:203], v[44:47]
	v_mfma_f32_16x16x32_bf16 v[32:35], v[116:119], v[208:211], v[32:35]
	v_mfma_f32_16x16x32_bf16 v[28:31], v[150:153], v[208:211], v[28:31]
	v_mfma_f32_16x16x32_bf16 v[16:19], v[116:119], v[216:219], v[16:19]
	v_mfma_f32_16x16x32_bf16 v[12:15], v[150:153], v[216:219], v[12:15]
	v_mfma_f32_16x16x32_bf16 v[64:67], v[120:123], v[196:199], v[64:67]
	v_mfma_f32_16x16x32_bf16 v[60:63], v[154:157], v[196:199], v[60:63]
	v_mfma_f32_16x16x32_bf16 v[48:51], v[120:123], v[204:207], v[48:51]
	v_mfma_f32_16x16x32_bf16 v[44:47], v[154:157], v[204:207], v[44:47]
	v_mfma_f32_16x16x32_bf16 v[32:35], v[120:123], v[212:215], v[32:35]
	v_mfma_f32_16x16x32_bf16 v[28:31], v[154:157], v[212:215], v[28:31]
	v_mfma_f32_16x16x32_bf16 v[16:19], v[120:123], v[220:223], v[16:19]
	v_mfma_f32_16x16x32_bf16 v[12:15], v[154:157], v[220:223], v[12:15]
	v_mfma_f32_16x16x32_bf16 v[56:59], v[162:165], v[192:195], v[56:59]
	v_mfma_f32_16x16x32_bf16 v[52:55], v[184:187], v[192:195], v[52:55]
	v_mfma_f32_16x16x32_bf16 v[40:43], v[162:165], v[200:203], v[40:43]
	v_mfma_f32_16x16x32_bf16 v[36:39], v[184:187], v[200:203], v[36:39]
	v_mfma_f32_16x16x32_bf16 v[24:27], v[162:165], v[208:211], v[24:27]
	v_mfma_f32_16x16x32_bf16 v[20:23], v[184:187], v[208:211], v[20:23]
	v_mfma_f32_16x16x32_bf16 v[8:11], v[162:165], v[216:219], v[8:11]
	v_mfma_f32_16x16x32_bf16 v[4:7], v[184:187], v[216:219], v[4:7]
	v_mfma_f32_16x16x32_bf16 v[56:59], v[166:169], v[196:199], v[56:59]
	v_mfma_f32_16x16x32_bf16 v[52:55], v[188:191], v[196:199], v[52:55]
	v_mfma_f32_16x16x32_bf16 v[40:43], v[166:169], v[204:207], v[40:43]
	v_mfma_f32_16x16x32_bf16 v[36:39], v[188:191], v[204:207], v[36:39]
	v_mfma_f32_16x16x32_bf16 v[24:27], v[166:169], v[212:215], v[24:27]
	v_mfma_f32_16x16x32_bf16 v[20:23], v[188:191], v[212:215], v[20:23]
	v_mfma_f32_16x16x32_bf16 v[8:11], v[166:169], v[220:223], v[8:11]
	v_mfma_f32_16x16x32_bf16 v[4:7], v[188:191], v[220:223], v[4:7]
	s_barrier
	s_add_i32 s25, s25, 2
	s_add_u32 s23, s23, 0x100
	s_addc_u32 s24, s24, 0
	s_cmpk_gt_u32 s25, 0x53
	s_mov_b64 s[0:1], s[14:15]
	s_cbranch_scc0 .LBB0_822
	s_and_b64 vcc, exec, s[48:49]
	s_cbranch_vccz .LBB0_825
	s_barrier
